# peer_u token loop rewritten by hand: gathers for the next token issued progressively inside the body (after each expert row is consumed), scalar address math, transposed 8-lane reduction
# speedup vs baseline: 1.1341x; 1.0050x over previous
.LBB0_636:
	s_or_b64 exec, exec, s[14:15]
	s_lshl_b32 s4, s16, 1
	v_mov_b32_e32 v183, 0
	s_add_u32 s4, s94, s4
	v_lshlrev_b32_e32 v64, 5, v211
	v_mov_b32_e32 v65, v183
	s_addc_u32 s5, s95, 0
	v_mov_b32_e32 v173, v183
	v_lshl_add_u64 v[64:65], s[46:47], 0, v[64:65]
	v_lshlrev_b32_e32 v66, 2, v210
	v_mov_b32_e32 v67, v183
	v_or_b32_e32 v187, 32, v159
	v_or_b32_e32 v212, 64, v159
	v_or_b32_e32 v214, 0x60, v159
	v_or_b32_e32 v215, 0x80, v159
	v_or_b32_e32 v216, 0xa0, v159
	v_or_b32_e32 v217, 0xc0, v159
	v_or_b32_e32 v218, 0xe0, v159
	v_lshl_add_u64 v[180:181], s[4:5], 0, v[182:183]
	v_cmp_eq_u32_e32 vcc, 0, v211
	v_cmp_eq_u32_e64 s[14:15], 1, v211
	v_cmp_eq_u32_e64 s[16:17], 2, v211
	v_cmp_eq_u32_e64 s[18:19], 3, v211
	v_cmp_eq_u32_e64 s[20:21], 4, v211
	v_cmp_eq_u32_e64 s[22:23], 5, v211
	v_cmp_eq_u32_e64 s[24:25], 6, v211
	v_cmp_eq_u32_e64 s[26:27], 7, v211
	v_lshl_add_u64 v[184:185], s[38:39], 0, v[172:173]
	v_lshl_add_u64 v[188:189], v[64:65], 0, v[66:67]
	s_lshl_b32 s52, s33, 3
	s_mov_b64 s[4:5], 0
	s_mov_b32 s53, 0x10200
	v_mov_b32_e32 v190, v174
	v_readfirstlane_b32 s28, v174
	v_readlane_b32 s31, v252, 27
	v_lshlrev_b32_e32 v134, 5, v211
	v_lshlrev_b32_e32 v135, 5, v211
	v_lshl_add_u32 v135, v210, 2, v135
	v_and_b32_e32 v128, 1, v211
	v_and_b32_e32 v130, 2, v211
	v_cmp_ne_u32_e64 s[48:49], 0, v128
	v_cmp_ne_u32_e64 s[50:51], 0, v130
	s_nop 3
	s_lshl_b32 s31, s31, 8
	v_add_u32_e32 v134, s31, v134
	s_add_u32 s29, s28, 0x10000
	s_mov_b32 s30, 129
	s_add_u32 s31, s28, 0x200
	s_min_u32 s31, s31, s29
	s_lshl_b32 s31, s31, 9
	s_add_u32 s4, s38, s31
	s_addc_u32 s5, s39, 0
	global_load_dword v161, v172, s[4:5]
	global_load_dword v163, v172, s[4:5] offset:256
	s_waitcnt vmcnt(2)
	ds_bpermute_b32 v224, v159, v177
	ds_bpermute_b32 v225, v187, v177
	ds_bpermute_b32 v226, v212, v177
	ds_bpermute_b32 v227, v214, v177
	ds_bpermute_b32 v228, v215, v177
	ds_bpermute_b32 v229, v216, v177
	ds_bpermute_b32 v230, v217, v177
	ds_bpermute_b32 v231, v218, v177
	ds_bpermute_b32 v232, v159, v213
	ds_bpermute_b32 v233, v187, v213
	ds_bpermute_b32 v234, v212, v213
	ds_bpermute_b32 v235, v214, v213
	ds_bpermute_b32 v236, v215, v213
	ds_bpermute_b32 v237, v216, v213
	ds_bpermute_b32 v238, v217, v213
	ds_bpermute_b32 v239, v218, v213
	s_waitcnt lgkmcnt(0)
	v_lshl_add_u32 v224, v224, 7, v255
	v_lshl_add_u32 v225, v225, 7, v255
	v_lshl_add_u32 v226, v226, 7, v255
	v_lshl_add_u32 v227, v227, 7, v255
	v_lshl_add_u32 v228, v228, 7, v255
	v_lshl_add_u32 v229, v229, 7, v255
	v_lshl_add_u32 v230, v230, 7, v255
	v_lshl_add_u32 v231, v231, 7, v255
	v_lshl_add_u32 v232, v232, 7, v255
	v_lshl_add_u32 v233, v233, 7, v255
	v_lshl_add_u32 v234, v234, 7, v255
	v_lshl_add_u32 v235, v235, 7, v255
	v_lshl_add_u32 v236, v236, 7, v255
	v_lshl_add_u32 v237, v237, 7, v255
	v_lshl_add_u32 v238, v238, 7, v255
	v_lshl_add_u32 v239, v239, 7, v255
	global_load_dwordx4 v[64:67], v224, s[98:99]
	global_load_dwordx4 v[68:71], v225, s[98:99]
	global_load_dwordx4 v[72:75], v226, s[98:99]
	global_load_dwordx4 v[76:79], v227, s[98:99]
	global_load_dwordx4 v[80:83], v228, s[98:99]
	global_load_dwordx4 v[84:87], v229, s[98:99]
	global_load_dwordx4 v[88:91], v230, s[98:99]
	global_load_dwordx4 v[92:95], v231, s[98:99]
	global_load_dwordx4 v[96:99], v232, s[98:99]
	global_load_dwordx4 v[100:103], v233, s[98:99]
	global_load_dwordx4 v[104:107], v234, s[98:99]
	global_load_dwordx4 v[108:111], v235, s[98:99]
	global_load_dwordx4 v[112:115], v236, s[98:99]
	global_load_dwordx4 v[116:119], v237, s[98:99]
	global_load_dwordx4 v[120:123], v238, s[98:99]
	global_load_dwordx4 v[124:127], v239, s[98:99]
	s_waitcnt vmcnt(16)
.Lpu0_loop:
	s_waitcnt vmcnt(18)
	ds_bpermute_b32 v224, v159, v161
	ds_bpermute_b32 v225, v187, v161
	ds_bpermute_b32 v226, v212, v161
	ds_bpermute_b32 v227, v214, v161
	ds_bpermute_b32 v228, v215, v161
	ds_bpermute_b32 v229, v216, v161
	ds_bpermute_b32 v230, v217, v161
	ds_bpermute_b32 v231, v218, v161
	ds_bpermute_b32 v232, v159, v163
	ds_bpermute_b32 v233, v187, v163
	ds_bpermute_b32 v234, v212, v163
	ds_bpermute_b32 v235, v214, v163
	ds_bpermute_b32 v236, v215, v163
	ds_bpermute_b32 v237, v216, v163
	ds_bpermute_b32 v238, v217, v163
	ds_bpermute_b32 v239, v218, v163
	v_lshlrev_b32_e32 v190, 16, v148
	v_and_b32_e32 v191, 0xffff0000, v148
	v_lshlrev_b32_e32 v192, 16, v149
	v_and_b32_e32 v193, 0xffff0000, v149
	v_lshlrev_b32_e32 v194, 16, v150
	v_and_b32_e32 v195, 0xffff0000, v150
	v_lshlrev_b32_e32 v196, 16, v151
	v_and_b32_e32 v197, 0xffff0000, v151
	v_lshlrev_b32_e32 v198, 16, v144
	v_and_b32_e32 v199, 0xffff0000, v144
	v_lshlrev_b32_e32 v200, 16, v145
	v_and_b32_e32 v201, 0xffff0000, v145
	v_lshlrev_b32_e32 v202, 16, v146
	v_and_b32_e32 v203, 0xffff0000, v146
	v_lshlrev_b32_e32 v220, 16, v147
	v_and_b32_e32 v221, 0xffff0000, v147
	s_waitcnt lgkmcnt(0)
	v_lshl_add_u32 v224, v224, 7, v255
	v_lshl_add_u32 v225, v225, 7, v255
	v_lshl_add_u32 v226, v226, 7, v255
	v_lshl_add_u32 v227, v227, 7, v255
	v_lshl_add_u32 v228, v228, 7, v255
	v_lshl_add_u32 v229, v229, 7, v255
	v_lshl_add_u32 v230, v230, 7, v255
	v_lshl_add_u32 v231, v231, 7, v255
	v_lshl_add_u32 v232, v232, 7, v255
	v_lshl_add_u32 v233, v233, 7, v255
	v_lshl_add_u32 v234, v234, 7, v255
	v_lshl_add_u32 v235, v235, 7, v255
	v_lshl_add_u32 v236, v236, 7, v255
	v_lshl_add_u32 v237, v237, 7, v255
	v_lshl_add_u32 v238, v238, 7, v255
	v_lshl_add_u32 v239, v239, 7, v255
	s_add_u32 s31, s28, 0x200
	s_min_u32 s31, s31, s29
	s_lshl_b32 s31, s31, 11
	s_add_u32 s4, s94, s31
	s_addc_u32 s5, s95, 0
	global_load_dwordx4 v[148:151], v134, s[4:5]
	global_load_dwordx4 v[144:147], v134, s[4:5] offset:16
	s_add_u32 s31, s28, 0x200
	s_min_u32 s31, s31, s29
	s_add_u32 s31, s31, 0x100
	s_lshl_b32 s31, s31, 9
	s_add_u32 s4, s38, s31
	s_addc_u32 s5, s39, 0
	global_load_dword v177, v172, s[4:5]
	global_load_dword v213, v172, s[4:5] offset:256
	v_cvt_pk_f32_fp8_sdwa v[130:131], v0 src0_sel:WORD_1
	v_cvt_pk_f32_fp8_e32 v[128:129], v0
	v_pk_mul_f32 v[130:131], v[130:131], v[192:193]
	v_cvt_pk_f32_fp8_e32 v[132:133], v1
	v_pk_fma_f32 v[250:251], v[128:129], v[190:191], v[130:131]
	v_cvt_pk_f32_fp8_sdwa v[128:129], v1 src0_sel:WORD_1
	v_pk_fma_f32 v[250:251], v[132:133], v[194:195], v[250:251]
	v_cvt_pk_f32_fp8_e32 v[132:133], v2
	v_pk_fma_f32 v[250:251], v[128:129], v[196:197], v[250:251]
	v_cvt_pk_f32_fp8_sdwa v[128:129], v2 src0_sel:WORD_1
	v_pk_fma_f32 v[250:251], v[132:133], v[198:199], v[250:251]
	v_cvt_pk_f32_fp8_e32 v[132:133], v3
	v_pk_fma_f32 v[250:251], v[128:129], v[200:201], v[250:251]
	v_cvt_pk_f32_fp8_sdwa v[128:129], v3 src0_sel:WORD_1
	v_pk_fma_f32 v[250:251], v[132:133], v[202:203], v[250:251]
	global_load_dwordx4 v[0:3], v224, s[98:99]
	v_pk_fma_f32 v[250:251], v[128:129], v[220:221], v[250:251]
	v_cvt_pk_f32_fp8_sdwa v[130:131], v4 src0_sel:WORD_1
	v_add_f32_e32 v240, v250, v251
	v_cvt_pk_f32_fp8_e32 v[128:129], v4
	v_pk_mul_f32 v[130:131], v[130:131], v[192:193]
	v_cvt_pk_f32_fp8_e32 v[132:133], v5
	v_pk_fma_f32 v[250:251], v[128:129], v[190:191], v[130:131]
	v_cvt_pk_f32_fp8_sdwa v[128:129], v5 src0_sel:WORD_1
	v_pk_fma_f32 v[250:251], v[132:133], v[194:195], v[250:251]
	v_cvt_pk_f32_fp8_e32 v[132:133], v6
	v_pk_fma_f32 v[250:251], v[128:129], v[196:197], v[250:251]
	v_cvt_pk_f32_fp8_sdwa v[128:129], v6 src0_sel:WORD_1
	v_pk_fma_f32 v[250:251], v[132:133], v[198:199], v[250:251]
	v_cvt_pk_f32_fp8_e32 v[132:133], v7
	v_pk_fma_f32 v[250:251], v[128:129], v[200:201], v[250:251]
	v_cvt_pk_f32_fp8_sdwa v[128:129], v7 src0_sel:WORD_1
	v_pk_fma_f32 v[250:251], v[132:133], v[202:203], v[250:251]
	global_load_dwordx4 v[4:7], v225, s[98:99]
	v_pk_fma_f32 v[250:251], v[128:129], v[220:221], v[250:251]
	v_cvt_pk_f32_fp8_sdwa v[130:131], v8 src0_sel:WORD_1
	v_add_f32_e32 v241, v250, v251
	v_cvt_pk_f32_fp8_e32 v[128:129], v8
	v_pk_mul_f32 v[130:131], v[130:131], v[192:193]
	v_cvt_pk_f32_fp8_e32 v[132:133], v9
	v_pk_fma_f32 v[250:251], v[128:129], v[190:191], v[130:131]
	v_cvt_pk_f32_fp8_sdwa v[128:129], v9 src0_sel:WORD_1
	v_pk_fma_f32 v[250:251], v[132:133], v[194:195], v[250:251]
	v_cvt_pk_f32_fp8_e32 v[132:133], v10
	v_pk_fma_f32 v[250:251], v[128:129], v[196:197], v[250:251]
	v_cvt_pk_f32_fp8_sdwa v[128:129], v10 src0_sel:WORD_1
	v_pk_fma_f32 v[250:251], v[132:133], v[198:199], v[250:251]
	v_cvt_pk_f32_fp8_e32 v[132:133], v11
	v_pk_fma_f32 v[250:251], v[128:129], v[200:201], v[250:251]
	v_cvt_pk_f32_fp8_sdwa v[128:129], v11 src0_sel:WORD_1
	v_pk_fma_f32 v[250:251], v[132:133], v[202:203], v[250:251]
	global_load_dwordx4 v[8:11], v226, s[98:99]
	v_pk_fma_f32 v[250:251], v[128:129], v[220:221], v[250:251]
	v_cvt_pk_f32_fp8_sdwa v[130:131], v12 src0_sel:WORD_1
	v_add_f32_e32 v242, v250, v251
	v_cvt_pk_f32_fp8_e32 v[128:129], v12
	v_pk_mul_f32 v[130:131], v[130:131], v[192:193]
	v_cvt_pk_f32_fp8_e32 v[132:133], v13
	v_pk_fma_f32 v[250:251], v[128:129], v[190:191], v[130:131]
	v_cvt_pk_f32_fp8_sdwa v[128:129], v13 src0_sel:WORD_1
	v_pk_fma_f32 v[250:251], v[132:133], v[194:195], v[250:251]
	v_cvt_pk_f32_fp8_e32 v[132:133], v14
	v_pk_fma_f32 v[250:251], v[128:129], v[196:197], v[250:251]
	v_cvt_pk_f32_fp8_sdwa v[128:129], v14 src0_sel:WORD_1
	v_pk_fma_f32 v[250:251], v[132:133], v[198:199], v[250:251]
	v_cvt_pk_f32_fp8_e32 v[132:133], v15
	v_pk_fma_f32 v[250:251], v[128:129], v[200:201], v[250:251]
	v_cvt_pk_f32_fp8_sdwa v[128:129], v15 src0_sel:WORD_1
	v_pk_fma_f32 v[250:251], v[132:133], v[202:203], v[250:251]
	global_load_dwordx4 v[12:15], v227, s[98:99]
	v_pk_fma_f32 v[250:251], v[128:129], v[220:221], v[250:251]
	v_cvt_pk_f32_fp8_sdwa v[130:131], v16 src0_sel:WORD_1
	v_add_f32_e32 v243, v250, v251
	v_cvt_pk_f32_fp8_e32 v[128:129], v16
	v_pk_mul_f32 v[130:131], v[130:131], v[192:193]
	v_cvt_pk_f32_fp8_e32 v[132:133], v17
	v_pk_fma_f32 v[250:251], v[128:129], v[190:191], v[130:131]
	v_cvt_pk_f32_fp8_sdwa v[128:129], v17 src0_sel:WORD_1
	v_pk_fma_f32 v[250:251], v[132:133], v[194:195], v[250:251]
	v_cvt_pk_f32_fp8_e32 v[132:133], v18
	v_pk_fma_f32 v[250:251], v[128:129], v[196:197], v[250:251]
	v_cvt_pk_f32_fp8_sdwa v[128:129], v18 src0_sel:WORD_1
	v_pk_fma_f32 v[250:251], v[132:133], v[198:199], v[250:251]
	v_cvt_pk_f32_fp8_e32 v[132:133], v19
	v_pk_fma_f32 v[250:251], v[128:129], v[200:201], v[250:251]
	v_cvt_pk_f32_fp8_sdwa v[128:129], v19 src0_sel:WORD_1
	v_pk_fma_f32 v[250:251], v[132:133], v[202:203], v[250:251]
	global_load_dwordx4 v[16:19], v228, s[98:99]
	v_pk_fma_f32 v[250:251], v[128:129], v[220:221], v[250:251]
	v_cvt_pk_f32_fp8_sdwa v[130:131], v20 src0_sel:WORD_1
	v_add_f32_e32 v244, v250, v251
	v_cvt_pk_f32_fp8_e32 v[128:129], v20
	v_pk_mul_f32 v[130:131], v[130:131], v[192:193]
	v_cvt_pk_f32_fp8_e32 v[132:133], v21
	v_pk_fma_f32 v[250:251], v[128:129], v[190:191], v[130:131]
	v_cvt_pk_f32_fp8_sdwa v[128:129], v21 src0_sel:WORD_1
	v_pk_fma_f32 v[250:251], v[132:133], v[194:195], v[250:251]
	v_cvt_pk_f32_fp8_e32 v[132:133], v22
	v_pk_fma_f32 v[250:251], v[128:129], v[196:197], v[250:251]
	v_cvt_pk_f32_fp8_sdwa v[128:129], v22 src0_sel:WORD_1
	v_pk_fma_f32 v[250:251], v[132:133], v[198:199], v[250:251]
	v_cvt_pk_f32_fp8_e32 v[132:133], v23
	v_pk_fma_f32 v[250:251], v[128:129], v[200:201], v[250:251]
	v_cvt_pk_f32_fp8_sdwa v[128:129], v23 src0_sel:WORD_1
	v_pk_fma_f32 v[250:251], v[132:133], v[202:203], v[250:251]
	global_load_dwordx4 v[20:23], v229, s[98:99]
	v_pk_fma_f32 v[250:251], v[128:129], v[220:221], v[250:251]
	v_cvt_pk_f32_fp8_sdwa v[130:131], v24 src0_sel:WORD_1
	v_add_f32_e32 v245, v250, v251
	v_add_f32_dpp v240, v240, v240 row_half_mirror row_mask:0xf bank_mask:0x5
	v_add_f32_dpp v240, v244, v244 row_half_mirror row_mask:0xf bank_mask:0xa
	v_cvt_pk_f32_fp8_e32 v[128:129], v24
	v_pk_mul_f32 v[130:131], v[130:131], v[192:193]
	v_cvt_pk_f32_fp8_e32 v[132:133], v25
	v_pk_fma_f32 v[250:251], v[128:129], v[190:191], v[130:131]
	v_cvt_pk_f32_fp8_sdwa v[128:129], v25 src0_sel:WORD_1
	v_pk_fma_f32 v[250:251], v[132:133], v[194:195], v[250:251]
	v_cvt_pk_f32_fp8_e32 v[132:133], v26
	v_pk_fma_f32 v[250:251], v[128:129], v[196:197], v[250:251]
	v_cvt_pk_f32_fp8_sdwa v[128:129], v26 src0_sel:WORD_1
	v_pk_fma_f32 v[250:251], v[132:133], v[198:199], v[250:251]
	v_cvt_pk_f32_fp8_e32 v[132:133], v27
	v_pk_fma_f32 v[250:251], v[128:129], v[200:201], v[250:251]
	v_cvt_pk_f32_fp8_sdwa v[128:129], v27 src0_sel:WORD_1
	v_pk_fma_f32 v[250:251], v[132:133], v[202:203], v[250:251]
	global_load_dwordx4 v[24:27], v230, s[98:99]
	v_pk_fma_f32 v[250:251], v[128:129], v[220:221], v[250:251]
	v_cvt_pk_f32_fp8_sdwa v[130:131], v28 src0_sel:WORD_1
	v_add_f32_e32 v246, v250, v251
	v_add_f32_dpp v241, v241, v241 row_half_mirror row_mask:0xf bank_mask:0x5
	v_add_f32_dpp v241, v245, v245 row_half_mirror row_mask:0xf bank_mask:0xa
	v_cvt_pk_f32_fp8_e32 v[128:129], v28
	v_pk_mul_f32 v[130:131], v[130:131], v[192:193]
	v_cvt_pk_f32_fp8_e32 v[132:133], v29
	v_pk_fma_f32 v[250:251], v[128:129], v[190:191], v[130:131]
	v_cvt_pk_f32_fp8_sdwa v[128:129], v29 src0_sel:WORD_1
	v_pk_fma_f32 v[250:251], v[132:133], v[194:195], v[250:251]
	v_cvt_pk_f32_fp8_e32 v[132:133], v30
	v_pk_fma_f32 v[250:251], v[128:129], v[196:197], v[250:251]
	v_cvt_pk_f32_fp8_sdwa v[128:129], v30 src0_sel:WORD_1
	v_pk_fma_f32 v[250:251], v[132:133], v[198:199], v[250:251]
	v_cvt_pk_f32_fp8_e32 v[132:133], v31
	v_pk_fma_f32 v[250:251], v[128:129], v[200:201], v[250:251]
	v_cvt_pk_f32_fp8_sdwa v[128:129], v31 src0_sel:WORD_1
	v_pk_fma_f32 v[250:251], v[132:133], v[202:203], v[250:251]
	global_load_dwordx4 v[28:31], v231, s[98:99]
	v_pk_fma_f32 v[250:251], v[128:129], v[220:221], v[250:251]
	v_cvt_pk_f32_fp8_sdwa v[130:131], v32 src0_sel:WORD_1
	v_add_f32_e32 v247, v250, v251
	v_add_f32_dpp v242, v242, v242 row_half_mirror row_mask:0xf bank_mask:0x5
	v_add_f32_dpp v242, v246, v246 row_half_mirror row_mask:0xf bank_mask:0xa
	v_add_f32_dpp v243, v243, v243 row_half_mirror row_mask:0xf bank_mask:0x5
	v_add_f32_dpp v243, v247, v247 row_half_mirror row_mask:0xf bank_mask:0xa
	v_add_f32_dpp v240, v240, v240 quad_perm:[2,3,0,1] row_mask:0xf bank_mask:0xf
	v_add_f32_dpp v242, v242, v242 quad_perm:[2,3,0,1] row_mask:0xf bank_mask:0xf
	v_add_f32_dpp v241, v241, v241 quad_perm:[2,3,0,1] row_mask:0xf bank_mask:0xf
	v_cndmask_b32_e64 v240, v240, v242, s[50:51]
	v_add_f32_dpp v243, v243, v243 quad_perm:[2,3,0,1] row_mask:0xf bank_mask:0xf
	v_cndmask_b32_e64 v241, v241, v243, s[50:51]
	v_add_f32_dpp v240, v240, v240 quad_perm:[1,0,3,2] row_mask:0xf bank_mask:0xf
	s_nop 0
	v_add_f32_dpp v241, v241, v241 quad_perm:[1,0,3,2] row_mask:0xf bank_mask:0xf
	v_cndmask_b32_e64 v248, v240, v241, s[48:49]
	v_cvt_pk_f32_fp8_e32 v[128:129], v32
	v_pk_mul_f32 v[130:131], v[130:131], v[192:193]
	v_cvt_pk_f32_fp8_e32 v[132:133], v33
	v_pk_fma_f32 v[250:251], v[128:129], v[190:191], v[130:131]
	v_cvt_pk_f32_fp8_sdwa v[128:129], v33 src0_sel:WORD_1
	v_pk_fma_f32 v[250:251], v[132:133], v[194:195], v[250:251]
	v_cvt_pk_f32_fp8_e32 v[132:133], v34
	v_pk_fma_f32 v[250:251], v[128:129], v[196:197], v[250:251]
	v_cvt_pk_f32_fp8_sdwa v[128:129], v34 src0_sel:WORD_1
	v_pk_fma_f32 v[250:251], v[132:133], v[198:199], v[250:251]
	v_cvt_pk_f32_fp8_e32 v[132:133], v35
	v_pk_fma_f32 v[250:251], v[128:129], v[200:201], v[250:251]
	v_cvt_pk_f32_fp8_sdwa v[128:129], v35 src0_sel:WORD_1
	v_pk_fma_f32 v[250:251], v[132:133], v[202:203], v[250:251]
	global_load_dwordx4 v[32:35], v232, s[98:99]
	v_pk_fma_f32 v[250:251], v[128:129], v[220:221], v[250:251]
	v_cvt_pk_f32_fp8_sdwa v[130:131], v36 src0_sel:WORD_1
	v_add_f32_e32 v240, v250, v251
	v_cvt_pk_f32_fp8_e32 v[128:129], v36
	v_pk_mul_f32 v[130:131], v[130:131], v[192:193]
	v_cvt_pk_f32_fp8_e32 v[132:133], v37
	v_pk_fma_f32 v[250:251], v[128:129], v[190:191], v[130:131]
	v_cvt_pk_f32_fp8_sdwa v[128:129], v37 src0_sel:WORD_1
	v_pk_fma_f32 v[250:251], v[132:133], v[194:195], v[250:251]
	v_cvt_pk_f32_fp8_e32 v[132:133], v38
	v_pk_fma_f32 v[250:251], v[128:129], v[196:197], v[250:251]
	v_cvt_pk_f32_fp8_sdwa v[128:129], v38 src0_sel:WORD_1
	v_pk_fma_f32 v[250:251], v[132:133], v[198:199], v[250:251]
	v_cvt_pk_f32_fp8_e32 v[132:133], v39
	v_pk_fma_f32 v[250:251], v[128:129], v[200:201], v[250:251]
	v_cvt_pk_f32_fp8_sdwa v[128:129], v39 src0_sel:WORD_1
	v_pk_fma_f32 v[250:251], v[132:133], v[202:203], v[250:251]
	global_load_dwordx4 v[36:39], v233, s[98:99]
	v_pk_fma_f32 v[250:251], v[128:129], v[220:221], v[250:251]
	v_cvt_pk_f32_fp8_sdwa v[130:131], v40 src0_sel:WORD_1
	v_add_f32_e32 v241, v250, v251
	v_cvt_pk_f32_fp8_e32 v[128:129], v40
	v_pk_mul_f32 v[130:131], v[130:131], v[192:193]
	v_cvt_pk_f32_fp8_e32 v[132:133], v41
	v_pk_fma_f32 v[250:251], v[128:129], v[190:191], v[130:131]
	v_cvt_pk_f32_fp8_sdwa v[128:129], v41 src0_sel:WORD_1
	v_pk_fma_f32 v[250:251], v[132:133], v[194:195], v[250:251]
	v_cvt_pk_f32_fp8_e32 v[132:133], v42
	v_pk_fma_f32 v[250:251], v[128:129], v[196:197], v[250:251]
	v_cvt_pk_f32_fp8_sdwa v[128:129], v42 src0_sel:WORD_1
	v_pk_fma_f32 v[250:251], v[132:133], v[198:199], v[250:251]
	v_cvt_pk_f32_fp8_e32 v[132:133], v43
	v_pk_fma_f32 v[250:251], v[128:129], v[200:201], v[250:251]
	v_cvt_pk_f32_fp8_sdwa v[128:129], v43 src0_sel:WORD_1
	v_pk_fma_f32 v[250:251], v[132:133], v[202:203], v[250:251]
	global_load_dwordx4 v[40:43], v234, s[98:99]
	v_pk_fma_f32 v[250:251], v[128:129], v[220:221], v[250:251]
	v_cvt_pk_f32_fp8_sdwa v[130:131], v44 src0_sel:WORD_1
	v_add_f32_e32 v242, v250, v251
	v_cvt_pk_f32_fp8_e32 v[128:129], v44
	v_pk_mul_f32 v[130:131], v[130:131], v[192:193]
	v_cvt_pk_f32_fp8_e32 v[132:133], v45
	v_pk_fma_f32 v[250:251], v[128:129], v[190:191], v[130:131]
	v_cvt_pk_f32_fp8_sdwa v[128:129], v45 src0_sel:WORD_1
	v_pk_fma_f32 v[250:251], v[132:133], v[194:195], v[250:251]
	v_cvt_pk_f32_fp8_e32 v[132:133], v46
	v_pk_fma_f32 v[250:251], v[128:129], v[196:197], v[250:251]
	v_cvt_pk_f32_fp8_sdwa v[128:129], v46 src0_sel:WORD_1
	v_pk_fma_f32 v[250:251], v[132:133], v[198:199], v[250:251]
	v_cvt_pk_f32_fp8_e32 v[132:133], v47
	v_pk_fma_f32 v[250:251], v[128:129], v[200:201], v[250:251]
	v_cvt_pk_f32_fp8_sdwa v[128:129], v47 src0_sel:WORD_1
	v_pk_fma_f32 v[250:251], v[132:133], v[202:203], v[250:251]
	global_load_dwordx4 v[44:47], v235, s[98:99]
	v_pk_fma_f32 v[250:251], v[128:129], v[220:221], v[250:251]
	v_cvt_pk_f32_fp8_sdwa v[130:131], v48 src0_sel:WORD_1
	v_add_f32_e32 v243, v250, v251
	v_cvt_pk_f32_fp8_e32 v[128:129], v48
	v_pk_mul_f32 v[130:131], v[130:131], v[192:193]
	v_cvt_pk_f32_fp8_e32 v[132:133], v49
	v_pk_fma_f32 v[250:251], v[128:129], v[190:191], v[130:131]
	v_cvt_pk_f32_fp8_sdwa v[128:129], v49 src0_sel:WORD_1
	v_pk_fma_f32 v[250:251], v[132:133], v[194:195], v[250:251]
	v_cvt_pk_f32_fp8_e32 v[132:133], v50
	v_pk_fma_f32 v[250:251], v[128:129], v[196:197], v[250:251]
	v_cvt_pk_f32_fp8_sdwa v[128:129], v50 src0_sel:WORD_1
	v_pk_fma_f32 v[250:251], v[132:133], v[198:199], v[250:251]
	v_cvt_pk_f32_fp8_e32 v[132:133], v51
	v_pk_fma_f32 v[250:251], v[128:129], v[200:201], v[250:251]
	v_cvt_pk_f32_fp8_sdwa v[128:129], v51 src0_sel:WORD_1
	v_pk_fma_f32 v[250:251], v[132:133], v[202:203], v[250:251]
	global_load_dwordx4 v[48:51], v236, s[98:99]
	v_pk_fma_f32 v[250:251], v[128:129], v[220:221], v[250:251]
	v_cvt_pk_f32_fp8_sdwa v[130:131], v52 src0_sel:WORD_1
	v_add_f32_e32 v244, v250, v251
	v_cvt_pk_f32_fp8_e32 v[128:129], v52
	v_pk_mul_f32 v[130:131], v[130:131], v[192:193]
	v_cvt_pk_f32_fp8_e32 v[132:133], v53
	v_pk_fma_f32 v[250:251], v[128:129], v[190:191], v[130:131]
	v_cvt_pk_f32_fp8_sdwa v[128:129], v53 src0_sel:WORD_1
	v_pk_fma_f32 v[250:251], v[132:133], v[194:195], v[250:251]
	v_cvt_pk_f32_fp8_e32 v[132:133], v54
	v_pk_fma_f32 v[250:251], v[128:129], v[196:197], v[250:251]
	v_cvt_pk_f32_fp8_sdwa v[128:129], v54 src0_sel:WORD_1
	v_pk_fma_f32 v[250:251], v[132:133], v[198:199], v[250:251]
	v_cvt_pk_f32_fp8_e32 v[132:133], v55
	v_pk_fma_f32 v[250:251], v[128:129], v[200:201], v[250:251]
	v_cvt_pk_f32_fp8_sdwa v[128:129], v55 src0_sel:WORD_1
	v_pk_fma_f32 v[250:251], v[132:133], v[202:203], v[250:251]
	global_load_dwordx4 v[52:55], v237, s[98:99]
	v_pk_fma_f32 v[250:251], v[128:129], v[220:221], v[250:251]
	v_cvt_pk_f32_fp8_sdwa v[130:131], v56 src0_sel:WORD_1
	v_add_f32_e32 v245, v250, v251
	v_add_f32_dpp v240, v240, v240 row_half_mirror row_mask:0xf bank_mask:0x5
	v_add_f32_dpp v240, v244, v244 row_half_mirror row_mask:0xf bank_mask:0xa
	v_cvt_pk_f32_fp8_e32 v[128:129], v56
	v_pk_mul_f32 v[130:131], v[130:131], v[192:193]
	v_cvt_pk_f32_fp8_e32 v[132:133], v57
	v_pk_fma_f32 v[250:251], v[128:129], v[190:191], v[130:131]
	v_cvt_pk_f32_fp8_sdwa v[128:129], v57 src0_sel:WORD_1
	v_pk_fma_f32 v[250:251], v[132:133], v[194:195], v[250:251]
	v_cvt_pk_f32_fp8_e32 v[132:133], v58
	v_pk_fma_f32 v[250:251], v[128:129], v[196:197], v[250:251]
	v_cvt_pk_f32_fp8_sdwa v[128:129], v58 src0_sel:WORD_1
	v_pk_fma_f32 v[250:251], v[132:133], v[198:199], v[250:251]
	v_cvt_pk_f32_fp8_e32 v[132:133], v59
	v_pk_fma_f32 v[250:251], v[128:129], v[200:201], v[250:251]
	v_cvt_pk_f32_fp8_sdwa v[128:129], v59 src0_sel:WORD_1
	v_pk_fma_f32 v[250:251], v[132:133], v[202:203], v[250:251]
	global_load_dwordx4 v[56:59], v238, s[98:99]
	v_pk_fma_f32 v[250:251], v[128:129], v[220:221], v[250:251]
	v_cvt_pk_f32_fp8_sdwa v[130:131], v60 src0_sel:WORD_1
	v_add_f32_e32 v246, v250, v251
	v_add_f32_dpp v241, v241, v241 row_half_mirror row_mask:0xf bank_mask:0x5
	v_add_f32_dpp v241, v245, v245 row_half_mirror row_mask:0xf bank_mask:0xa
	v_add_f32_dpp v242, v242, v242 row_half_mirror row_mask:0xf bank_mask:0x5
	v_add_f32_dpp v242, v246, v246 row_half_mirror row_mask:0xf bank_mask:0xa
	v_add_f32_dpp v240, v240, v240 quad_perm:[2,3,0,1] row_mask:0xf bank_mask:0xf
	v_add_f32_dpp v241, v241, v241 quad_perm:[2,3,0,1] row_mask:0xf bank_mask:0xf
	v_add_f32_dpp v242, v242, v242 quad_perm:[2,3,0,1] row_mask:0xf bank_mask:0xf
	v_cndmask_b32_e64 v240, v240, v242, s[50:51]
	v_cvt_pk_f32_fp8_e32 v[128:129], v60
	v_pk_mul_f32 v[130:131], v[130:131], v[192:193]
	v_cvt_pk_f32_fp8_e32 v[132:133], v61
	v_pk_fma_f32 v[250:251], v[128:129], v[190:191], v[130:131]
	v_cvt_pk_f32_fp8_sdwa v[128:129], v61 src0_sel:WORD_1
	v_pk_fma_f32 v[250:251], v[132:133], v[194:195], v[250:251]
	v_cvt_pk_f32_fp8_e32 v[132:133], v62
	v_pk_fma_f32 v[250:251], v[128:129], v[196:197], v[250:251]
	v_cvt_pk_f32_fp8_sdwa v[128:129], v62 src0_sel:WORD_1
	v_pk_fma_f32 v[250:251], v[132:133], v[198:199], v[250:251]
	v_cvt_pk_f32_fp8_e32 v[132:133], v63
	v_pk_fma_f32 v[250:251], v[128:129], v[200:201], v[250:251]
	v_cvt_pk_f32_fp8_sdwa v[128:129], v63 src0_sel:WORD_1
	v_pk_fma_f32 v[250:251], v[132:133], v[202:203], v[250:251]
	global_load_dwordx4 v[60:63], v239, s[98:99]
	v_pk_fma_f32 v[250:251], v[128:129], v[220:221], v[250:251]
	s_nop 0
	v_add_f32_e32 v247, v250, v251
	v_add_f32_dpp v240, v240, v240 quad_perm:[1,0,3,2] row_mask:0xf bank_mask:0xf
	v_add_f32_dpp v243, v243, v243 row_half_mirror row_mask:0xf bank_mask:0x5
	v_add_f32_dpp v243, v247, v247 row_half_mirror row_mask:0xf bank_mask:0xa
	s_nop 1
	v_add_f32_dpp v243, v243, v243 quad_perm:[2,3,0,1] row_mask:0xf bank_mask:0xf
	v_cndmask_b32_e64 v241, v241, v243, s[50:51]
	s_nop 1
	v_add_f32_dpp v241, v241, v241 quad_perm:[1,0,3,2] row_mask:0xf bank_mask:0xf
	v_cndmask_b32_e64 v249, v240, v241, s[48:49]
	s_mov_b32 s31, s28
	s_lshl_b32 s31, s31, 9
	s_add_u32 s4, s46, s31
	s_addc_u32 s5, s47, 0
	global_store_dword v135, v248, s[4:5]
	global_store_dword v135, v249, s[4:5] offset:256
	s_waitcnt vmcnt(18)
	ds_bpermute_b32 v224, v159, v177
	ds_bpermute_b32 v225, v187, v177
	ds_bpermute_b32 v226, v212, v177
	ds_bpermute_b32 v227, v214, v177
	ds_bpermute_b32 v228, v215, v177
	ds_bpermute_b32 v229, v216, v177
	ds_bpermute_b32 v230, v217, v177
	ds_bpermute_b32 v231, v218, v177
	ds_bpermute_b32 v232, v159, v213
	ds_bpermute_b32 v233, v187, v213
	ds_bpermute_b32 v234, v212, v213
	ds_bpermute_b32 v235, v214, v213
	ds_bpermute_b32 v236, v215, v213
	ds_bpermute_b32 v237, v216, v213
	ds_bpermute_b32 v238, v217, v213
	ds_bpermute_b32 v239, v218, v213
	v_lshlrev_b32_e32 v190, 16, v140
	v_and_b32_e32 v191, 0xffff0000, v140
	v_lshlrev_b32_e32 v192, 16, v141
	v_and_b32_e32 v193, 0xffff0000, v141
	v_lshlrev_b32_e32 v194, 16, v142
	v_and_b32_e32 v195, 0xffff0000, v142
	v_lshlrev_b32_e32 v196, 16, v143
	v_and_b32_e32 v197, 0xffff0000, v143
	v_lshlrev_b32_e32 v198, 16, v136
	v_and_b32_e32 v199, 0xffff0000, v136
	v_lshlrev_b32_e32 v200, 16, v137
	v_and_b32_e32 v201, 0xffff0000, v137
	v_lshlrev_b32_e32 v202, 16, v138
	v_and_b32_e32 v203, 0xffff0000, v138
	v_lshlrev_b32_e32 v220, 16, v139
	v_and_b32_e32 v221, 0xffff0000, v139
	s_waitcnt lgkmcnt(0)
	v_lshl_add_u32 v224, v224, 7, v255
	v_lshl_add_u32 v225, v225, 7, v255
	v_lshl_add_u32 v226, v226, 7, v255
	v_lshl_add_u32 v227, v227, 7, v255
	v_lshl_add_u32 v228, v228, 7, v255
	v_lshl_add_u32 v229, v229, 7, v255
	v_lshl_add_u32 v230, v230, 7, v255
	v_lshl_add_u32 v231, v231, 7, v255
	v_lshl_add_u32 v232, v232, 7, v255
	v_lshl_add_u32 v233, v233, 7, v255
	v_lshl_add_u32 v234, v234, 7, v255
	v_lshl_add_u32 v235, v235, 7, v255
	v_lshl_add_u32 v236, v236, 7, v255
	v_lshl_add_u32 v237, v237, 7, v255
	v_lshl_add_u32 v238, v238, 7, v255
	v_lshl_add_u32 v239, v239, 7, v255
	s_add_u32 s31, s28, 0x200
	s_min_u32 s31, s31, s29
	s_add_u32 s31, s31, 0x100
	s_lshl_b32 s31, s31, 11
	s_add_u32 s4, s94, s31
	s_addc_u32 s5, s95, 0
	global_load_dwordx4 v[140:143], v134, s[4:5]
	global_load_dwordx4 v[136:139], v134, s[4:5] offset:16
	s_add_u32 s31, s28, 0x400
	s_min_u32 s31, s31, s29
	s_lshl_b32 s31, s31, 9
	s_add_u32 s4, s38, s31
	s_addc_u32 s5, s39, 0
	global_load_dword v161, v172, s[4:5]
	global_load_dword v163, v172, s[4:5] offset:256
	v_cvt_pk_f32_fp8_sdwa v[130:131], v64 src0_sel:WORD_1
	v_cvt_pk_f32_fp8_e32 v[128:129], v64
	v_pk_mul_f32 v[130:131], v[130:131], v[192:193]
	v_cvt_pk_f32_fp8_e32 v[132:133], v65
	v_pk_fma_f32 v[250:251], v[128:129], v[190:191], v[130:131]
	v_cvt_pk_f32_fp8_sdwa v[128:129], v65 src0_sel:WORD_1
	v_pk_fma_f32 v[250:251], v[132:133], v[194:195], v[250:251]
	v_cvt_pk_f32_fp8_e32 v[132:133], v66
	v_pk_fma_f32 v[250:251], v[128:129], v[196:197], v[250:251]
	v_cvt_pk_f32_fp8_sdwa v[128:129], v66 src0_sel:WORD_1
	v_pk_fma_f32 v[250:251], v[132:133], v[198:199], v[250:251]
	v_cvt_pk_f32_fp8_e32 v[132:133], v67
	v_pk_fma_f32 v[250:251], v[128:129], v[200:201], v[250:251]
	v_cvt_pk_f32_fp8_sdwa v[128:129], v67 src0_sel:WORD_1
	v_pk_fma_f32 v[250:251], v[132:133], v[202:203], v[250:251]
	global_load_dwordx4 v[64:67], v224, s[98:99]
	v_pk_fma_f32 v[250:251], v[128:129], v[220:221], v[250:251]
	v_cvt_pk_f32_fp8_sdwa v[130:131], v68 src0_sel:WORD_1
	v_add_f32_e32 v240, v250, v251
	v_cvt_pk_f32_fp8_e32 v[128:129], v68
	v_pk_mul_f32 v[130:131], v[130:131], v[192:193]
	v_cvt_pk_f32_fp8_e32 v[132:133], v69
	v_pk_fma_f32 v[250:251], v[128:129], v[190:191], v[130:131]
	v_cvt_pk_f32_fp8_sdwa v[128:129], v69 src0_sel:WORD_1
	v_pk_fma_f32 v[250:251], v[132:133], v[194:195], v[250:251]
	v_cvt_pk_f32_fp8_e32 v[132:133], v70
	v_pk_fma_f32 v[250:251], v[128:129], v[196:197], v[250:251]
	v_cvt_pk_f32_fp8_sdwa v[128:129], v70 src0_sel:WORD_1
	v_pk_fma_f32 v[250:251], v[132:133], v[198:199], v[250:251]
	v_cvt_pk_f32_fp8_e32 v[132:133], v71
	v_pk_fma_f32 v[250:251], v[128:129], v[200:201], v[250:251]
	v_cvt_pk_f32_fp8_sdwa v[128:129], v71 src0_sel:WORD_1
	v_pk_fma_f32 v[250:251], v[132:133], v[202:203], v[250:251]
	global_load_dwordx4 v[68:71], v225, s[98:99]
	v_pk_fma_f32 v[250:251], v[128:129], v[220:221], v[250:251]
	v_cvt_pk_f32_fp8_sdwa v[130:131], v72 src0_sel:WORD_1
	v_add_f32_e32 v241, v250, v251
	v_cvt_pk_f32_fp8_e32 v[128:129], v72
	v_pk_mul_f32 v[130:131], v[130:131], v[192:193]
	v_cvt_pk_f32_fp8_e32 v[132:133], v73
	v_pk_fma_f32 v[250:251], v[128:129], v[190:191], v[130:131]
	v_cvt_pk_f32_fp8_sdwa v[128:129], v73 src0_sel:WORD_1
	v_pk_fma_f32 v[250:251], v[132:133], v[194:195], v[250:251]
	v_cvt_pk_f32_fp8_e32 v[132:133], v74
	v_pk_fma_f32 v[250:251], v[128:129], v[196:197], v[250:251]
	v_cvt_pk_f32_fp8_sdwa v[128:129], v74 src0_sel:WORD_1
	v_pk_fma_f32 v[250:251], v[132:133], v[198:199], v[250:251]
	v_cvt_pk_f32_fp8_e32 v[132:133], v75
	v_pk_fma_f32 v[250:251], v[128:129], v[200:201], v[250:251]
	v_cvt_pk_f32_fp8_sdwa v[128:129], v75 src0_sel:WORD_1
	v_pk_fma_f32 v[250:251], v[132:133], v[202:203], v[250:251]
	global_load_dwordx4 v[72:75], v226, s[98:99]
	v_pk_fma_f32 v[250:251], v[128:129], v[220:221], v[250:251]
	v_cvt_pk_f32_fp8_sdwa v[130:131], v76 src0_sel:WORD_1
	v_add_f32_e32 v242, v250, v251
	v_cvt_pk_f32_fp8_e32 v[128:129], v76
	v_pk_mul_f32 v[130:131], v[130:131], v[192:193]
	v_cvt_pk_f32_fp8_e32 v[132:133], v77
	v_pk_fma_f32 v[250:251], v[128:129], v[190:191], v[130:131]
	v_cvt_pk_f32_fp8_sdwa v[128:129], v77 src0_sel:WORD_1
	v_pk_fma_f32 v[250:251], v[132:133], v[194:195], v[250:251]
	v_cvt_pk_f32_fp8_e32 v[132:133], v78
	v_pk_fma_f32 v[250:251], v[128:129], v[196:197], v[250:251]
	v_cvt_pk_f32_fp8_sdwa v[128:129], v78 src0_sel:WORD_1
	v_pk_fma_f32 v[250:251], v[132:133], v[198:199], v[250:251]
	v_cvt_pk_f32_fp8_e32 v[132:133], v79
	v_pk_fma_f32 v[250:251], v[128:129], v[200:201], v[250:251]
	v_cvt_pk_f32_fp8_sdwa v[128:129], v79 src0_sel:WORD_1
	v_pk_fma_f32 v[250:251], v[132:133], v[202:203], v[250:251]
	global_load_dwordx4 v[76:79], v227, s[98:99]
	v_pk_fma_f32 v[250:251], v[128:129], v[220:221], v[250:251]
	v_cvt_pk_f32_fp8_sdwa v[130:131], v80 src0_sel:WORD_1
	v_add_f32_e32 v243, v250, v251
	v_cvt_pk_f32_fp8_e32 v[128:129], v80
	v_pk_mul_f32 v[130:131], v[130:131], v[192:193]
	v_cvt_pk_f32_fp8_e32 v[132:133], v81
	v_pk_fma_f32 v[250:251], v[128:129], v[190:191], v[130:131]
	v_cvt_pk_f32_fp8_sdwa v[128:129], v81 src0_sel:WORD_1
	v_pk_fma_f32 v[250:251], v[132:133], v[194:195], v[250:251]
	v_cvt_pk_f32_fp8_e32 v[132:133], v82
	v_pk_fma_f32 v[250:251], v[128:129], v[196:197], v[250:251]
	v_cvt_pk_f32_fp8_sdwa v[128:129], v82 src0_sel:WORD_1
	v_pk_fma_f32 v[250:251], v[132:133], v[198:199], v[250:251]
	v_cvt_pk_f32_fp8_e32 v[132:133], v83
	v_pk_fma_f32 v[250:251], v[128:129], v[200:201], v[250:251]
	v_cvt_pk_f32_fp8_sdwa v[128:129], v83 src0_sel:WORD_1
	v_pk_fma_f32 v[250:251], v[132:133], v[202:203], v[250:251]
	global_load_dwordx4 v[80:83], v228, s[98:99]
	v_pk_fma_f32 v[250:251], v[128:129], v[220:221], v[250:251]
	v_cvt_pk_f32_fp8_sdwa v[130:131], v84 src0_sel:WORD_1
	v_add_f32_e32 v244, v250, v251
	v_cvt_pk_f32_fp8_e32 v[128:129], v84
	v_pk_mul_f32 v[130:131], v[130:131], v[192:193]
	v_cvt_pk_f32_fp8_e32 v[132:133], v85
	v_pk_fma_f32 v[250:251], v[128:129], v[190:191], v[130:131]
	v_cvt_pk_f32_fp8_sdwa v[128:129], v85 src0_sel:WORD_1
	v_pk_fma_f32 v[250:251], v[132:133], v[194:195], v[250:251]
	v_cvt_pk_f32_fp8_e32 v[132:133], v86
	v_pk_fma_f32 v[250:251], v[128:129], v[196:197], v[250:251]
	v_cvt_pk_f32_fp8_sdwa v[128:129], v86 src0_sel:WORD_1
	v_pk_fma_f32 v[250:251], v[132:133], v[198:199], v[250:251]
	v_cvt_pk_f32_fp8_e32 v[132:133], v87
	v_pk_fma_f32 v[250:251], v[128:129], v[200:201], v[250:251]
	v_cvt_pk_f32_fp8_sdwa v[128:129], v87 src0_sel:WORD_1
	v_pk_fma_f32 v[250:251], v[132:133], v[202:203], v[250:251]
	global_load_dwordx4 v[84:87], v229, s[98:99]
	v_pk_fma_f32 v[250:251], v[128:129], v[220:221], v[250:251]
	v_cvt_pk_f32_fp8_sdwa v[130:131], v88 src0_sel:WORD_1
	v_add_f32_e32 v245, v250, v251
	v_add_f32_dpp v240, v240, v240 row_half_mirror row_mask:0xf bank_mask:0x5
	v_add_f32_dpp v240, v244, v244 row_half_mirror row_mask:0xf bank_mask:0xa
	v_cvt_pk_f32_fp8_e32 v[128:129], v88
	v_pk_mul_f32 v[130:131], v[130:131], v[192:193]
	v_cvt_pk_f32_fp8_e32 v[132:133], v89
	v_pk_fma_f32 v[250:251], v[128:129], v[190:191], v[130:131]
	v_cvt_pk_f32_fp8_sdwa v[128:129], v89 src0_sel:WORD_1
	v_pk_fma_f32 v[250:251], v[132:133], v[194:195], v[250:251]
	v_cvt_pk_f32_fp8_e32 v[132:133], v90
	v_pk_fma_f32 v[250:251], v[128:129], v[196:197], v[250:251]
	v_cvt_pk_f32_fp8_sdwa v[128:129], v90 src0_sel:WORD_1
	v_pk_fma_f32 v[250:251], v[132:133], v[198:199], v[250:251]
	v_cvt_pk_f32_fp8_e32 v[132:133], v91
	v_pk_fma_f32 v[250:251], v[128:129], v[200:201], v[250:251]
	v_cvt_pk_f32_fp8_sdwa v[128:129], v91 src0_sel:WORD_1
	v_pk_fma_f32 v[250:251], v[132:133], v[202:203], v[250:251]
	global_load_dwordx4 v[88:91], v230, s[98:99]
	v_pk_fma_f32 v[250:251], v[128:129], v[220:221], v[250:251]
	v_cvt_pk_f32_fp8_sdwa v[130:131], v92 src0_sel:WORD_1
	v_add_f32_e32 v246, v250, v251
	v_add_f32_dpp v241, v241, v241 row_half_mirror row_mask:0xf bank_mask:0x5
	v_add_f32_dpp v241, v245, v245 row_half_mirror row_mask:0xf bank_mask:0xa
	v_cvt_pk_f32_fp8_e32 v[128:129], v92
	v_pk_mul_f32 v[130:131], v[130:131], v[192:193]
	v_cvt_pk_f32_fp8_e32 v[132:133], v93
	v_pk_fma_f32 v[250:251], v[128:129], v[190:191], v[130:131]
	v_cvt_pk_f32_fp8_sdwa v[128:129], v93 src0_sel:WORD_1
	v_pk_fma_f32 v[250:251], v[132:133], v[194:195], v[250:251]
	v_cvt_pk_f32_fp8_e32 v[132:133], v94
	v_pk_fma_f32 v[250:251], v[128:129], v[196:197], v[250:251]
	v_cvt_pk_f32_fp8_sdwa v[128:129], v94 src0_sel:WORD_1
	v_pk_fma_f32 v[250:251], v[132:133], v[198:199], v[250:251]
	v_cvt_pk_f32_fp8_e32 v[132:133], v95
	v_pk_fma_f32 v[250:251], v[128:129], v[200:201], v[250:251]
	v_cvt_pk_f32_fp8_sdwa v[128:129], v95 src0_sel:WORD_1
	v_pk_fma_f32 v[250:251], v[132:133], v[202:203], v[250:251]
	global_load_dwordx4 v[92:95], v231, s[98:99]
	v_pk_fma_f32 v[250:251], v[128:129], v[220:221], v[250:251]
	v_cvt_pk_f32_fp8_sdwa v[130:131], v96 src0_sel:WORD_1
	v_add_f32_e32 v247, v250, v251
	v_add_f32_dpp v242, v242, v242 row_half_mirror row_mask:0xf bank_mask:0x5
	v_add_f32_dpp v242, v246, v246 row_half_mirror row_mask:0xf bank_mask:0xa
	v_add_f32_dpp v243, v243, v243 row_half_mirror row_mask:0xf bank_mask:0x5
	v_add_f32_dpp v243, v247, v247 row_half_mirror row_mask:0xf bank_mask:0xa
	v_add_f32_dpp v240, v240, v240 quad_perm:[2,3,0,1] row_mask:0xf bank_mask:0xf
	v_add_f32_dpp v242, v242, v242 quad_perm:[2,3,0,1] row_mask:0xf bank_mask:0xf
	v_add_f32_dpp v241, v241, v241 quad_perm:[2,3,0,1] row_mask:0xf bank_mask:0xf
	v_cndmask_b32_e64 v240, v240, v242, s[50:51]
	v_add_f32_dpp v243, v243, v243 quad_perm:[2,3,0,1] row_mask:0xf bank_mask:0xf
	v_cndmask_b32_e64 v241, v241, v243, s[50:51]
	v_add_f32_dpp v240, v240, v240 quad_perm:[1,0,3,2] row_mask:0xf bank_mask:0xf
	s_nop 0
	v_add_f32_dpp v241, v241, v241 quad_perm:[1,0,3,2] row_mask:0xf bank_mask:0xf
	v_cndmask_b32_e64 v248, v240, v241, s[48:49]
	v_cvt_pk_f32_fp8_e32 v[128:129], v96
	v_pk_mul_f32 v[130:131], v[130:131], v[192:193]
	v_cvt_pk_f32_fp8_e32 v[132:133], v97
	v_pk_fma_f32 v[250:251], v[128:129], v[190:191], v[130:131]
	v_cvt_pk_f32_fp8_sdwa v[128:129], v97 src0_sel:WORD_1
	v_pk_fma_f32 v[250:251], v[132:133], v[194:195], v[250:251]
	v_cvt_pk_f32_fp8_e32 v[132:133], v98
	v_pk_fma_f32 v[250:251], v[128:129], v[196:197], v[250:251]
	v_cvt_pk_f32_fp8_sdwa v[128:129], v98 src0_sel:WORD_1
	v_pk_fma_f32 v[250:251], v[132:133], v[198:199], v[250:251]
	v_cvt_pk_f32_fp8_e32 v[132:133], v99
	v_pk_fma_f32 v[250:251], v[128:129], v[200:201], v[250:251]
	v_cvt_pk_f32_fp8_sdwa v[128:129], v99 src0_sel:WORD_1
	v_pk_fma_f32 v[250:251], v[132:133], v[202:203], v[250:251]
	global_load_dwordx4 v[96:99], v232, s[98:99]
	v_pk_fma_f32 v[250:251], v[128:129], v[220:221], v[250:251]
	v_cvt_pk_f32_fp8_sdwa v[130:131], v100 src0_sel:WORD_1
	v_add_f32_e32 v240, v250, v251
	v_cvt_pk_f32_fp8_e32 v[128:129], v100
	v_pk_mul_f32 v[130:131], v[130:131], v[192:193]
	v_cvt_pk_f32_fp8_e32 v[132:133], v101
	v_pk_fma_f32 v[250:251], v[128:129], v[190:191], v[130:131]
	v_cvt_pk_f32_fp8_sdwa v[128:129], v101 src0_sel:WORD_1
	v_pk_fma_f32 v[250:251], v[132:133], v[194:195], v[250:251]
	v_cvt_pk_f32_fp8_e32 v[132:133], v102
	v_pk_fma_f32 v[250:251], v[128:129], v[196:197], v[250:251]
	v_cvt_pk_f32_fp8_sdwa v[128:129], v102 src0_sel:WORD_1
	v_pk_fma_f32 v[250:251], v[132:133], v[198:199], v[250:251]
	v_cvt_pk_f32_fp8_e32 v[132:133], v103
	v_pk_fma_f32 v[250:251], v[128:129], v[200:201], v[250:251]
	v_cvt_pk_f32_fp8_sdwa v[128:129], v103 src0_sel:WORD_1
	v_pk_fma_f32 v[250:251], v[132:133], v[202:203], v[250:251]
	global_load_dwordx4 v[100:103], v233, s[98:99]
	v_pk_fma_f32 v[250:251], v[128:129], v[220:221], v[250:251]
	v_cvt_pk_f32_fp8_sdwa v[130:131], v104 src0_sel:WORD_1
	v_add_f32_e32 v241, v250, v251
	v_cvt_pk_f32_fp8_e32 v[128:129], v104
	v_pk_mul_f32 v[130:131], v[130:131], v[192:193]
	v_cvt_pk_f32_fp8_e32 v[132:133], v105
	v_pk_fma_f32 v[250:251], v[128:129], v[190:191], v[130:131]
	v_cvt_pk_f32_fp8_sdwa v[128:129], v105 src0_sel:WORD_1
	v_pk_fma_f32 v[250:251], v[132:133], v[194:195], v[250:251]
	v_cvt_pk_f32_fp8_e32 v[132:133], v106
	v_pk_fma_f32 v[250:251], v[128:129], v[196:197], v[250:251]
	v_cvt_pk_f32_fp8_sdwa v[128:129], v106 src0_sel:WORD_1
	v_pk_fma_f32 v[250:251], v[132:133], v[198:199], v[250:251]
	v_cvt_pk_f32_fp8_e32 v[132:133], v107
	v_pk_fma_f32 v[250:251], v[128:129], v[200:201], v[250:251]
	v_cvt_pk_f32_fp8_sdwa v[128:129], v107 src0_sel:WORD_1
	v_pk_fma_f32 v[250:251], v[132:133], v[202:203], v[250:251]
	global_load_dwordx4 v[104:107], v234, s[98:99]
	v_pk_fma_f32 v[250:251], v[128:129], v[220:221], v[250:251]
	v_cvt_pk_f32_fp8_sdwa v[130:131], v108 src0_sel:WORD_1
	v_add_f32_e32 v242, v250, v251
	v_cvt_pk_f32_fp8_e32 v[128:129], v108
	v_pk_mul_f32 v[130:131], v[130:131], v[192:193]
	v_cvt_pk_f32_fp8_e32 v[132:133], v109
	v_pk_fma_f32 v[250:251], v[128:129], v[190:191], v[130:131]
	v_cvt_pk_f32_fp8_sdwa v[128:129], v109 src0_sel:WORD_1
	v_pk_fma_f32 v[250:251], v[132:133], v[194:195], v[250:251]
	v_cvt_pk_f32_fp8_e32 v[132:133], v110
	v_pk_fma_f32 v[250:251], v[128:129], v[196:197], v[250:251]
	v_cvt_pk_f32_fp8_sdwa v[128:129], v110 src0_sel:WORD_1
	v_pk_fma_f32 v[250:251], v[132:133], v[198:199], v[250:251]
	v_cvt_pk_f32_fp8_e32 v[132:133], v111
	v_pk_fma_f32 v[250:251], v[128:129], v[200:201], v[250:251]
	v_cvt_pk_f32_fp8_sdwa v[128:129], v111 src0_sel:WORD_1
	v_pk_fma_f32 v[250:251], v[132:133], v[202:203], v[250:251]
	global_load_dwordx4 v[108:111], v235, s[98:99]
	v_pk_fma_f32 v[250:251], v[128:129], v[220:221], v[250:251]
	v_cvt_pk_f32_fp8_sdwa v[130:131], v112 src0_sel:WORD_1
	v_add_f32_e32 v243, v250, v251
	v_cvt_pk_f32_fp8_e32 v[128:129], v112
	v_pk_mul_f32 v[130:131], v[130:131], v[192:193]
	v_cvt_pk_f32_fp8_e32 v[132:133], v113
	v_pk_fma_f32 v[250:251], v[128:129], v[190:191], v[130:131]
	v_cvt_pk_f32_fp8_sdwa v[128:129], v113 src0_sel:WORD_1
	v_pk_fma_f32 v[250:251], v[132:133], v[194:195], v[250:251]
	v_cvt_pk_f32_fp8_e32 v[132:133], v114
	v_pk_fma_f32 v[250:251], v[128:129], v[196:197], v[250:251]
	v_cvt_pk_f32_fp8_sdwa v[128:129], v114 src0_sel:WORD_1
	v_pk_fma_f32 v[250:251], v[132:133], v[198:199], v[250:251]
	v_cvt_pk_f32_fp8_e32 v[132:133], v115
	v_pk_fma_f32 v[250:251], v[128:129], v[200:201], v[250:251]
	v_cvt_pk_f32_fp8_sdwa v[128:129], v115 src0_sel:WORD_1
	v_pk_fma_f32 v[250:251], v[132:133], v[202:203], v[250:251]
	global_load_dwordx4 v[112:115], v236, s[98:99]
	v_pk_fma_f32 v[250:251], v[128:129], v[220:221], v[250:251]
	v_cvt_pk_f32_fp8_sdwa v[130:131], v116 src0_sel:WORD_1
	v_add_f32_e32 v244, v250, v251
	v_cvt_pk_f32_fp8_e32 v[128:129], v116
	v_pk_mul_f32 v[130:131], v[130:131], v[192:193]
	v_cvt_pk_f32_fp8_e32 v[132:133], v117
	v_pk_fma_f32 v[250:251], v[128:129], v[190:191], v[130:131]
	v_cvt_pk_f32_fp8_sdwa v[128:129], v117 src0_sel:WORD_1
	v_pk_fma_f32 v[250:251], v[132:133], v[194:195], v[250:251]
	v_cvt_pk_f32_fp8_e32 v[132:133], v118
	v_pk_fma_f32 v[250:251], v[128:129], v[196:197], v[250:251]
	v_cvt_pk_f32_fp8_sdwa v[128:129], v118 src0_sel:WORD_1
	v_pk_fma_f32 v[250:251], v[132:133], v[198:199], v[250:251]
	v_cvt_pk_f32_fp8_e32 v[132:133], v119
	v_pk_fma_f32 v[250:251], v[128:129], v[200:201], v[250:251]
	v_cvt_pk_f32_fp8_sdwa v[128:129], v119 src0_sel:WORD_1
	v_pk_fma_f32 v[250:251], v[132:133], v[202:203], v[250:251]
	global_load_dwordx4 v[116:119], v237, s[98:99]
	v_pk_fma_f32 v[250:251], v[128:129], v[220:221], v[250:251]
	v_cvt_pk_f32_fp8_sdwa v[130:131], v120 src0_sel:WORD_1
	v_add_f32_e32 v245, v250, v251
	v_add_f32_dpp v240, v240, v240 row_half_mirror row_mask:0xf bank_mask:0x5
	v_add_f32_dpp v240, v244, v244 row_half_mirror row_mask:0xf bank_mask:0xa
	v_cvt_pk_f32_fp8_e32 v[128:129], v120
	v_pk_mul_f32 v[130:131], v[130:131], v[192:193]
	v_cvt_pk_f32_fp8_e32 v[132:133], v121
	v_pk_fma_f32 v[250:251], v[128:129], v[190:191], v[130:131]
	v_cvt_pk_f32_fp8_sdwa v[128:129], v121 src0_sel:WORD_1
	v_pk_fma_f32 v[250:251], v[132:133], v[194:195], v[250:251]
	v_cvt_pk_f32_fp8_e32 v[132:133], v122
	v_pk_fma_f32 v[250:251], v[128:129], v[196:197], v[250:251]
	v_cvt_pk_f32_fp8_sdwa v[128:129], v122 src0_sel:WORD_1
	v_pk_fma_f32 v[250:251], v[132:133], v[198:199], v[250:251]
	v_cvt_pk_f32_fp8_e32 v[132:133], v123
	v_pk_fma_f32 v[250:251], v[128:129], v[200:201], v[250:251]
	v_cvt_pk_f32_fp8_sdwa v[128:129], v123 src0_sel:WORD_1
	v_pk_fma_f32 v[250:251], v[132:133], v[202:203], v[250:251]
	global_load_dwordx4 v[120:123], v238, s[98:99]
	v_pk_fma_f32 v[250:251], v[128:129], v[220:221], v[250:251]
	v_cvt_pk_f32_fp8_sdwa v[130:131], v124 src0_sel:WORD_1
	v_add_f32_e32 v246, v250, v251
	v_add_f32_dpp v241, v241, v241 row_half_mirror row_mask:0xf bank_mask:0x5
	v_add_f32_dpp v241, v245, v245 row_half_mirror row_mask:0xf bank_mask:0xa
	v_add_f32_dpp v242, v242, v242 row_half_mirror row_mask:0xf bank_mask:0x5
	v_add_f32_dpp v242, v246, v246 row_half_mirror row_mask:0xf bank_mask:0xa
	v_add_f32_dpp v240, v240, v240 quad_perm:[2,3,0,1] row_mask:0xf bank_mask:0xf
	v_add_f32_dpp v241, v241, v241 quad_perm:[2,3,0,1] row_mask:0xf bank_mask:0xf
	v_add_f32_dpp v242, v242, v242 quad_perm:[2,3,0,1] row_mask:0xf bank_mask:0xf
	v_cndmask_b32_e64 v240, v240, v242, s[50:51]
	v_cvt_pk_f32_fp8_e32 v[128:129], v124
	v_pk_mul_f32 v[130:131], v[130:131], v[192:193]
	v_cvt_pk_f32_fp8_e32 v[132:133], v125
	v_pk_fma_f32 v[250:251], v[128:129], v[190:191], v[130:131]
	v_cvt_pk_f32_fp8_sdwa v[128:129], v125 src0_sel:WORD_1
	v_pk_fma_f32 v[250:251], v[132:133], v[194:195], v[250:251]
	v_cvt_pk_f32_fp8_e32 v[132:133], v126
	v_pk_fma_f32 v[250:251], v[128:129], v[196:197], v[250:251]
	v_cvt_pk_f32_fp8_sdwa v[128:129], v126 src0_sel:WORD_1
	v_pk_fma_f32 v[250:251], v[132:133], v[198:199], v[250:251]
	v_cvt_pk_f32_fp8_e32 v[132:133], v127
	v_pk_fma_f32 v[250:251], v[128:129], v[200:201], v[250:251]
	v_cvt_pk_f32_fp8_sdwa v[128:129], v127 src0_sel:WORD_1
	v_pk_fma_f32 v[250:251], v[132:133], v[202:203], v[250:251]
	global_load_dwordx4 v[124:127], v239, s[98:99]
	v_pk_fma_f32 v[250:251], v[128:129], v[220:221], v[250:251]
	s_nop 0
	v_add_f32_e32 v247, v250, v251
	v_add_f32_dpp v240, v240, v240 quad_perm:[1,0,3,2] row_mask:0xf bank_mask:0xf
	v_add_f32_dpp v243, v243, v243 row_half_mirror row_mask:0xf bank_mask:0x5
	v_add_f32_dpp v243, v247, v247 row_half_mirror row_mask:0xf bank_mask:0xa
	s_nop 1
	v_add_f32_dpp v243, v243, v243 quad_perm:[2,3,0,1] row_mask:0xf bank_mask:0xf
	v_cndmask_b32_e64 v241, v241, v243, s[50:51]
	s_nop 1
	v_add_f32_dpp v241, v241, v241 quad_perm:[1,0,3,2] row_mask:0xf bank_mask:0xf
	v_cndmask_b32_e64 v249, v240, v241, s[48:49]
	s_add_u32 s31, s28, 0x100
	s_lshl_b32 s31, s31, 9
	s_add_u32 s4, s46, s31
	s_addc_u32 s5, s47, 0
	global_store_dword v135, v248, s[4:5]
	global_store_dword v135, v249, s[4:5] offset:256
	s_add_u32 s28, s28, 0x200
	s_sub_u32 s30, s30, 1
	s_cmp_lg_u32 s30, 0
	s_cbranch_scc1 .Lpu0_loop

.LBB0_1098:
	s_or_b64 exec, exec, s[4:5]
	s_lshl_b32 s2, s6, 1
	s_add_u32 s2, s94, s2
	s_addc_u32 s3, s95, 0
	v_lshl_add_u64 v[162:163], s[2:3], 0, v[182:183]
	v_lshlrev_b32_e32 v182, 5, v211
	v_lshl_add_u64 v[56:57], s[46:47], 0, v[182:183]
	v_lshlrev_b32_e32 v182, 2, v210
	v_or_b32_e32 v194, 32, v157
	v_or_b32_e32 v196, 64, v157
	v_or_b32_e32 v197, 0x60, v157
	v_or_b32_e32 v198, 0x80, v157
	v_or_b32_e32 v199, 0xa0, v157
	v_or_b32_e32 v200, 0xc0, v157
	v_or_b32_e32 v201, 0xe0, v157
	v_cmp_eq_u32_e32 vcc, 0, v211
	v_cmp_eq_u32_e64 s[6:7], 1, v211
	v_cmp_eq_u32_e64 s[8:9], 2, v211
	v_cmp_eq_u32_e64 s[16:17], 3, v211
	v_cmp_eq_u32_e64 s[18:19], 4, v211
	v_cmp_eq_u32_e64 s[20:21], 5, v211
	v_cmp_eq_u32_e64 s[22:23], 6, v211
	v_cmp_eq_u32_e64 s[24:25], 7, v211
	v_lshl_add_u64 v[164:165], s[38:39], 0, v[172:173]
	v_lshl_add_u64 v[166:167], v[56:57], 0, v[182:183]
	s_lshl_b32 s42, s33, 3
	s_mov_b64 s[2:3], 0
	s_mov_b32 s43, 0x101ff
	v_mov_b32_e32 v168, v174
	v_readfirstlane_b32 s26, v174
	v_readlane_b32 s29, v252, 27
	v_lshlrev_b32_e32 v134, 5, v211
	v_lshlrev_b32_e32 v135, 5, v211
	v_lshl_add_u32 v135, v210, 2, v135
	v_and_b32_e32 v128, 1, v211
	v_and_b32_e32 v130, 2, v211
	v_cmp_ne_u32_e64 s[4:5], 0, v128
	v_cmp_ne_u32_e64 s[40:41], 0, v130
	s_nop 3
	s_lshl_b32 s29, s29, 8
	v_add_u32_e32 v134, s29, v134
	s_add_u32 s27, s26, 0x10000
	s_mov_b32 s28, 129
	s_add_u32 s29, s26, 0x200
	s_min_u32 s29, s29, s27
	s_lshl_b32 s29, s29, 9
	s_add_u32 s2, s38, s29
	s_addc_u32 s3, s39, 0
	global_load_dword v159, v172, s[2:3]
	global_load_dword v161, v172, s[2:3] offset:256
	s_waitcnt vmcnt(2)
	ds_bpermute_b32 v224, v157, v177
	ds_bpermute_b32 v225, v194, v177
	ds_bpermute_b32 v226, v196, v177
	ds_bpermute_b32 v227, v197, v177
	ds_bpermute_b32 v228, v198, v177
	ds_bpermute_b32 v229, v199, v177
	ds_bpermute_b32 v230, v200, v177
	ds_bpermute_b32 v231, v201, v177
	ds_bpermute_b32 v232, v157, v195
	ds_bpermute_b32 v233, v194, v195
	ds_bpermute_b32 v234, v196, v195
	ds_bpermute_b32 v235, v197, v195
	ds_bpermute_b32 v236, v198, v195
	ds_bpermute_b32 v237, v199, v195
	ds_bpermute_b32 v238, v200, v195
	ds_bpermute_b32 v239, v201, v195
	s_waitcnt lgkmcnt(0)
	v_lshl_add_u32 v224, v224, 7, v255
	v_lshl_add_u32 v225, v225, 7, v255
	v_lshl_add_u32 v226, v226, 7, v255
	v_lshl_add_u32 v227, v227, 7, v255
	v_lshl_add_u32 v228, v228, 7, v255
	v_lshl_add_u32 v229, v229, 7, v255
	v_lshl_add_u32 v230, v230, 7, v255
	v_lshl_add_u32 v231, v231, 7, v255
	v_lshl_add_u32 v232, v232, 7, v255
	v_lshl_add_u32 v233, v233, 7, v255
	v_lshl_add_u32 v234, v234, 7, v255
	v_lshl_add_u32 v235, v235, 7, v255
	v_lshl_add_u32 v236, v236, 7, v255
	v_lshl_add_u32 v237, v237, 7, v255
	v_lshl_add_u32 v238, v238, 7, v255
	v_lshl_add_u32 v239, v239, 7, v255
	global_load_dwordx4 v[56:59], v224, s[98:99]
	global_load_dwordx4 v[60:63], v225, s[98:99]
	global_load_dwordx4 v[72:75], v226, s[98:99]
	global_load_dwordx4 v[76:79], v227, s[98:99]
	global_load_dwordx4 v[80:83], v228, s[98:99]
	global_load_dwordx4 v[84:87], v229, s[98:99]
	global_load_dwordx4 v[88:91], v230, s[98:99]
	global_load_dwordx4 v[92:95], v231, s[98:99]
	global_load_dwordx4 v[96:99], v232, s[98:99]
	global_load_dwordx4 v[100:103], v233, s[98:99]
	global_load_dwordx4 v[104:107], v234, s[98:99]
	global_load_dwordx4 v[108:111], v235, s[98:99]
	global_load_dwordx4 v[112:115], v236, s[98:99]
	global_load_dwordx4 v[116:119], v237, s[98:99]
	global_load_dwordx4 v[120:123], v238, s[98:99]
	global_load_dwordx4 v[124:127], v239, s[98:99]
	s_waitcnt vmcnt(16)
.Lpu1_loop:
	s_waitcnt vmcnt(18)
	ds_bpermute_b32 v224, v157, v159
	ds_bpermute_b32 v225, v194, v159
	ds_bpermute_b32 v226, v196, v159
	ds_bpermute_b32 v227, v197, v159
	ds_bpermute_b32 v228, v198, v159
	ds_bpermute_b32 v229, v199, v159
	ds_bpermute_b32 v230, v200, v159
	ds_bpermute_b32 v231, v201, v159
	ds_bpermute_b32 v232, v157, v161
	ds_bpermute_b32 v233, v194, v161
	ds_bpermute_b32 v234, v196, v161
	ds_bpermute_b32 v235, v197, v161
	ds_bpermute_b32 v236, v198, v161
	ds_bpermute_b32 v237, v199, v161
	ds_bpermute_b32 v238, v200, v161
	ds_bpermute_b32 v239, v201, v161
	v_lshlrev_b32_e32 v186, 16, v148
	v_and_b32_e32 v187, 0xffff0000, v148
	v_lshlrev_b32_e32 v188, 16, v149
	v_and_b32_e32 v189, 0xffff0000, v149
	v_lshlrev_b32_e32 v190, 16, v150
	v_and_b32_e32 v191, 0xffff0000, v150
	v_lshlrev_b32_e32 v192, 16, v151
	v_and_b32_e32 v193, 0xffff0000, v151
	v_lshlrev_b32_e32 v202, 16, v144
	v_and_b32_e32 v203, 0xffff0000, v144
	v_lshlrev_b32_e32 v204, 16, v145
	v_and_b32_e32 v205, 0xffff0000, v145
	v_lshlrev_b32_e32 v206, 16, v146
	v_and_b32_e32 v207, 0xffff0000, v146
	v_lshlrev_b32_e32 v208, 16, v147
	v_and_b32_e32 v209, 0xffff0000, v147
	s_waitcnt lgkmcnt(0)
	v_lshl_add_u32 v224, v224, 7, v255
	v_lshl_add_u32 v225, v225, 7, v255
	v_lshl_add_u32 v226, v226, 7, v255
	v_lshl_add_u32 v227, v227, 7, v255
	v_lshl_add_u32 v228, v228, 7, v255
	v_lshl_add_u32 v229, v229, 7, v255
	v_lshl_add_u32 v230, v230, 7, v255
	v_lshl_add_u32 v231, v231, 7, v255
	v_lshl_add_u32 v232, v232, 7, v255
	v_lshl_add_u32 v233, v233, 7, v255
	v_lshl_add_u32 v234, v234, 7, v255
	v_lshl_add_u32 v235, v235, 7, v255
	v_lshl_add_u32 v236, v236, 7, v255
	v_lshl_add_u32 v237, v237, 7, v255
	v_lshl_add_u32 v238, v238, 7, v255
	v_lshl_add_u32 v239, v239, 7, v255
	s_add_u32 s29, s26, 0x200
	s_min_u32 s29, s29, s27
	s_lshl_b32 s29, s29, 11
	s_add_u32 s2, s94, s29
	s_addc_u32 s3, s95, 0
	global_load_dwordx4 v[148:151], v134, s[2:3]
	global_load_dwordx4 v[144:147], v134, s[2:3] offset:16
	s_add_u32 s29, s26, 0x200
	s_min_u32 s29, s29, s27
	s_add_u32 s29, s29, 0x100
	s_lshl_b32 s29, s29, 9
	s_add_u32 s2, s38, s29
	s_addc_u32 s3, s39, 0
	global_load_dword v177, v172, s[2:3]
	global_load_dword v195, v172, s[2:3] offset:256
	v_cvt_pk_f32_fp8_sdwa v[130:131], v0 src0_sel:WORD_1
	v_cvt_pk_f32_fp8_e32 v[128:129], v0
	v_pk_mul_f32 v[130:131], v[130:131], v[188:189]
	v_cvt_pk_f32_fp8_e32 v[132:133], v1
	v_pk_fma_f32 v[250:251], v[128:129], v[186:187], v[130:131]
	v_cvt_pk_f32_fp8_sdwa v[128:129], v1 src0_sel:WORD_1
	v_pk_fma_f32 v[250:251], v[132:133], v[190:191], v[250:251]
	v_cvt_pk_f32_fp8_e32 v[132:133], v2
	v_pk_fma_f32 v[250:251], v[128:129], v[192:193], v[250:251]
	v_cvt_pk_f32_fp8_sdwa v[128:129], v2 src0_sel:WORD_1
	v_pk_fma_f32 v[250:251], v[132:133], v[202:203], v[250:251]
	v_cvt_pk_f32_fp8_e32 v[132:133], v3
	v_pk_fma_f32 v[250:251], v[128:129], v[204:205], v[250:251]
	v_cvt_pk_f32_fp8_sdwa v[128:129], v3 src0_sel:WORD_1
	v_pk_fma_f32 v[250:251], v[132:133], v[206:207], v[250:251]
	global_load_dwordx4 v[0:3], v224, s[98:99]
	v_pk_fma_f32 v[250:251], v[128:129], v[208:209], v[250:251]
	v_cvt_pk_f32_fp8_sdwa v[130:131], v4 src0_sel:WORD_1
	v_add_f32_e32 v240, v250, v251
	v_cvt_pk_f32_fp8_e32 v[128:129], v4
	v_pk_mul_f32 v[130:131], v[130:131], v[188:189]
	v_cvt_pk_f32_fp8_e32 v[132:133], v5
	v_pk_fma_f32 v[250:251], v[128:129], v[186:187], v[130:131]
	v_cvt_pk_f32_fp8_sdwa v[128:129], v5 src0_sel:WORD_1
	v_pk_fma_f32 v[250:251], v[132:133], v[190:191], v[250:251]
	v_cvt_pk_f32_fp8_e32 v[132:133], v6
	v_pk_fma_f32 v[250:251], v[128:129], v[192:193], v[250:251]
	v_cvt_pk_f32_fp8_sdwa v[128:129], v6 src0_sel:WORD_1
	v_pk_fma_f32 v[250:251], v[132:133], v[202:203], v[250:251]
	v_cvt_pk_f32_fp8_e32 v[132:133], v7
	v_pk_fma_f32 v[250:251], v[128:129], v[204:205], v[250:251]
	v_cvt_pk_f32_fp8_sdwa v[128:129], v7 src0_sel:WORD_1
	v_pk_fma_f32 v[250:251], v[132:133], v[206:207], v[250:251]
	global_load_dwordx4 v[4:7], v225, s[98:99]
	v_pk_fma_f32 v[250:251], v[128:129], v[208:209], v[250:251]
	v_cvt_pk_f32_fp8_sdwa v[130:131], v8 src0_sel:WORD_1
	v_add_f32_e32 v241, v250, v251
	v_cvt_pk_f32_fp8_e32 v[128:129], v8
	v_pk_mul_f32 v[130:131], v[130:131], v[188:189]
	v_cvt_pk_f32_fp8_e32 v[132:133], v9
	v_pk_fma_f32 v[250:251], v[128:129], v[186:187], v[130:131]
	v_cvt_pk_f32_fp8_sdwa v[128:129], v9 src0_sel:WORD_1
	v_pk_fma_f32 v[250:251], v[132:133], v[190:191], v[250:251]
	v_cvt_pk_f32_fp8_e32 v[132:133], v10
	v_pk_fma_f32 v[250:251], v[128:129], v[192:193], v[250:251]
	v_cvt_pk_f32_fp8_sdwa v[128:129], v10 src0_sel:WORD_1
	v_pk_fma_f32 v[250:251], v[132:133], v[202:203], v[250:251]
	v_cvt_pk_f32_fp8_e32 v[132:133], v11
	v_pk_fma_f32 v[250:251], v[128:129], v[204:205], v[250:251]
	v_cvt_pk_f32_fp8_sdwa v[128:129], v11 src0_sel:WORD_1
	v_pk_fma_f32 v[250:251], v[132:133], v[206:207], v[250:251]
	global_load_dwordx4 v[8:11], v226, s[98:99]
	v_pk_fma_f32 v[250:251], v[128:129], v[208:209], v[250:251]
	v_cvt_pk_f32_fp8_sdwa v[130:131], v12 src0_sel:WORD_1
	v_add_f32_e32 v242, v250, v251
	v_cvt_pk_f32_fp8_e32 v[128:129], v12
	v_pk_mul_f32 v[130:131], v[130:131], v[188:189]
	v_cvt_pk_f32_fp8_e32 v[132:133], v13
	v_pk_fma_f32 v[250:251], v[128:129], v[186:187], v[130:131]
	v_cvt_pk_f32_fp8_sdwa v[128:129], v13 src0_sel:WORD_1
	v_pk_fma_f32 v[250:251], v[132:133], v[190:191], v[250:251]
	v_cvt_pk_f32_fp8_e32 v[132:133], v14
	v_pk_fma_f32 v[250:251], v[128:129], v[192:193], v[250:251]
	v_cvt_pk_f32_fp8_sdwa v[128:129], v14 src0_sel:WORD_1
	v_pk_fma_f32 v[250:251], v[132:133], v[202:203], v[250:251]
	v_cvt_pk_f32_fp8_e32 v[132:133], v15
	v_pk_fma_f32 v[250:251], v[128:129], v[204:205], v[250:251]
	v_cvt_pk_f32_fp8_sdwa v[128:129], v15 src0_sel:WORD_1
	v_pk_fma_f32 v[250:251], v[132:133], v[206:207], v[250:251]
	global_load_dwordx4 v[12:15], v227, s[98:99]
	v_pk_fma_f32 v[250:251], v[128:129], v[208:209], v[250:251]
	v_cvt_pk_f32_fp8_sdwa v[130:131], v16 src0_sel:WORD_1
	v_add_f32_e32 v243, v250, v251
	v_cvt_pk_f32_fp8_e32 v[128:129], v16
	v_pk_mul_f32 v[130:131], v[130:131], v[188:189]
	v_cvt_pk_f32_fp8_e32 v[132:133], v17
	v_pk_fma_f32 v[250:251], v[128:129], v[186:187], v[130:131]
	v_cvt_pk_f32_fp8_sdwa v[128:129], v17 src0_sel:WORD_1
	v_pk_fma_f32 v[250:251], v[132:133], v[190:191], v[250:251]
	v_cvt_pk_f32_fp8_e32 v[132:133], v18
	v_pk_fma_f32 v[250:251], v[128:129], v[192:193], v[250:251]
	v_cvt_pk_f32_fp8_sdwa v[128:129], v18 src0_sel:WORD_1
	v_pk_fma_f32 v[250:251], v[132:133], v[202:203], v[250:251]
	v_cvt_pk_f32_fp8_e32 v[132:133], v19
	v_pk_fma_f32 v[250:251], v[128:129], v[204:205], v[250:251]
	v_cvt_pk_f32_fp8_sdwa v[128:129], v19 src0_sel:WORD_1
	v_pk_fma_f32 v[250:251], v[132:133], v[206:207], v[250:251]
	global_load_dwordx4 v[16:19], v228, s[98:99]
	v_pk_fma_f32 v[250:251], v[128:129], v[208:209], v[250:251]
	v_cvt_pk_f32_fp8_sdwa v[130:131], v20 src0_sel:WORD_1
	v_add_f32_e32 v244, v250, v251
	v_cvt_pk_f32_fp8_e32 v[128:129], v20
	v_pk_mul_f32 v[130:131], v[130:131], v[188:189]
	v_cvt_pk_f32_fp8_e32 v[132:133], v21
	v_pk_fma_f32 v[250:251], v[128:129], v[186:187], v[130:131]
	v_cvt_pk_f32_fp8_sdwa v[128:129], v21 src0_sel:WORD_1
	v_pk_fma_f32 v[250:251], v[132:133], v[190:191], v[250:251]
	v_cvt_pk_f32_fp8_e32 v[132:133], v22
	v_pk_fma_f32 v[250:251], v[128:129], v[192:193], v[250:251]
	v_cvt_pk_f32_fp8_sdwa v[128:129], v22 src0_sel:WORD_1
	v_pk_fma_f32 v[250:251], v[132:133], v[202:203], v[250:251]
	v_cvt_pk_f32_fp8_e32 v[132:133], v23
	v_pk_fma_f32 v[250:251], v[128:129], v[204:205], v[250:251]
	v_cvt_pk_f32_fp8_sdwa v[128:129], v23 src0_sel:WORD_1
	v_pk_fma_f32 v[250:251], v[132:133], v[206:207], v[250:251]
	global_load_dwordx4 v[20:23], v229, s[98:99]
	v_pk_fma_f32 v[250:251], v[128:129], v[208:209], v[250:251]
	v_cvt_pk_f32_fp8_sdwa v[130:131], v24 src0_sel:WORD_1
	v_add_f32_e32 v245, v250, v251
	v_add_f32_dpp v240, v240, v240 row_half_mirror row_mask:0xf bank_mask:0x5
	v_add_f32_dpp v240, v244, v244 row_half_mirror row_mask:0xf bank_mask:0xa
	v_cvt_pk_f32_fp8_e32 v[128:129], v24
	v_pk_mul_f32 v[130:131], v[130:131], v[188:189]
	v_cvt_pk_f32_fp8_e32 v[132:133], v25
	v_pk_fma_f32 v[250:251], v[128:129], v[186:187], v[130:131]
	v_cvt_pk_f32_fp8_sdwa v[128:129], v25 src0_sel:WORD_1
	v_pk_fma_f32 v[250:251], v[132:133], v[190:191], v[250:251]
	v_cvt_pk_f32_fp8_e32 v[132:133], v26
	v_pk_fma_f32 v[250:251], v[128:129], v[192:193], v[250:251]
	v_cvt_pk_f32_fp8_sdwa v[128:129], v26 src0_sel:WORD_1
	v_pk_fma_f32 v[250:251], v[132:133], v[202:203], v[250:251]
	v_cvt_pk_f32_fp8_e32 v[132:133], v27
	v_pk_fma_f32 v[250:251], v[128:129], v[204:205], v[250:251]
	v_cvt_pk_f32_fp8_sdwa v[128:129], v27 src0_sel:WORD_1
	v_pk_fma_f32 v[250:251], v[132:133], v[206:207], v[250:251]
	global_load_dwordx4 v[24:27], v230, s[98:99]
	v_pk_fma_f32 v[250:251], v[128:129], v[208:209], v[250:251]
	v_cvt_pk_f32_fp8_sdwa v[130:131], v28 src0_sel:WORD_1
	v_add_f32_e32 v246, v250, v251
	v_add_f32_dpp v241, v241, v241 row_half_mirror row_mask:0xf bank_mask:0x5
	v_add_f32_dpp v241, v245, v245 row_half_mirror row_mask:0xf bank_mask:0xa
	v_cvt_pk_f32_fp8_e32 v[128:129], v28
	v_pk_mul_f32 v[130:131], v[130:131], v[188:189]
	v_cvt_pk_f32_fp8_e32 v[132:133], v29
	v_pk_fma_f32 v[250:251], v[128:129], v[186:187], v[130:131]
	v_cvt_pk_f32_fp8_sdwa v[128:129], v29 src0_sel:WORD_1
	v_pk_fma_f32 v[250:251], v[132:133], v[190:191], v[250:251]
	v_cvt_pk_f32_fp8_e32 v[132:133], v30
	v_pk_fma_f32 v[250:251], v[128:129], v[192:193], v[250:251]
	v_cvt_pk_f32_fp8_sdwa v[128:129], v30 src0_sel:WORD_1
	v_pk_fma_f32 v[250:251], v[132:133], v[202:203], v[250:251]
	v_cvt_pk_f32_fp8_e32 v[132:133], v31
	v_pk_fma_f32 v[250:251], v[128:129], v[204:205], v[250:251]
	v_cvt_pk_f32_fp8_sdwa v[128:129], v31 src0_sel:WORD_1
	v_pk_fma_f32 v[250:251], v[132:133], v[206:207], v[250:251]
	global_load_dwordx4 v[28:31], v231, s[98:99]
	v_pk_fma_f32 v[250:251], v[128:129], v[208:209], v[250:251]
	v_cvt_pk_f32_fp8_sdwa v[130:131], v32 src0_sel:WORD_1
	v_add_f32_e32 v247, v250, v251
	v_add_f32_dpp v242, v242, v242 row_half_mirror row_mask:0xf bank_mask:0x5
	v_add_f32_dpp v242, v246, v246 row_half_mirror row_mask:0xf bank_mask:0xa
	v_add_f32_dpp v243, v243, v243 row_half_mirror row_mask:0xf bank_mask:0x5
	v_add_f32_dpp v243, v247, v247 row_half_mirror row_mask:0xf bank_mask:0xa
	v_add_f32_dpp v240, v240, v240 quad_perm:[2,3,0,1] row_mask:0xf bank_mask:0xf
	v_add_f32_dpp v242, v242, v242 quad_perm:[2,3,0,1] row_mask:0xf bank_mask:0xf
	v_add_f32_dpp v241, v241, v241 quad_perm:[2,3,0,1] row_mask:0xf bank_mask:0xf
	v_cndmask_b32_e64 v240, v240, v242, s[40:41]
	v_add_f32_dpp v243, v243, v243 quad_perm:[2,3,0,1] row_mask:0xf bank_mask:0xf
	v_cndmask_b32_e64 v241, v241, v243, s[40:41]
	v_add_f32_dpp v240, v240, v240 quad_perm:[1,0,3,2] row_mask:0xf bank_mask:0xf
	s_nop 0
	v_add_f32_dpp v241, v241, v241 quad_perm:[1,0,3,2] row_mask:0xf bank_mask:0xf
	v_cndmask_b32_e64 v248, v240, v241, s[4:5]
	v_cvt_pk_f32_fp8_e32 v[128:129], v32
	v_pk_mul_f32 v[130:131], v[130:131], v[188:189]
	v_cvt_pk_f32_fp8_e32 v[132:133], v33
	v_pk_fma_f32 v[250:251], v[128:129], v[186:187], v[130:131]
	v_cvt_pk_f32_fp8_sdwa v[128:129], v33 src0_sel:WORD_1
	v_pk_fma_f32 v[250:251], v[132:133], v[190:191], v[250:251]
	v_cvt_pk_f32_fp8_e32 v[132:133], v34
	v_pk_fma_f32 v[250:251], v[128:129], v[192:193], v[250:251]
	v_cvt_pk_f32_fp8_sdwa v[128:129], v34 src0_sel:WORD_1
	v_pk_fma_f32 v[250:251], v[132:133], v[202:203], v[250:251]
	v_cvt_pk_f32_fp8_e32 v[132:133], v35
	v_pk_fma_f32 v[250:251], v[128:129], v[204:205], v[250:251]
	v_cvt_pk_f32_fp8_sdwa v[128:129], v35 src0_sel:WORD_1
	v_pk_fma_f32 v[250:251], v[132:133], v[206:207], v[250:251]
	global_load_dwordx4 v[32:35], v232, s[98:99]
	v_pk_fma_f32 v[250:251], v[128:129], v[208:209], v[250:251]
	v_cvt_pk_f32_fp8_sdwa v[130:131], v36 src0_sel:WORD_1
	v_add_f32_e32 v240, v250, v251
	v_cvt_pk_f32_fp8_e32 v[128:129], v36
	v_pk_mul_f32 v[130:131], v[130:131], v[188:189]
	v_cvt_pk_f32_fp8_e32 v[132:133], v37
	v_pk_fma_f32 v[250:251], v[128:129], v[186:187], v[130:131]
	v_cvt_pk_f32_fp8_sdwa v[128:129], v37 src0_sel:WORD_1
	v_pk_fma_f32 v[250:251], v[132:133], v[190:191], v[250:251]
	v_cvt_pk_f32_fp8_e32 v[132:133], v38
	v_pk_fma_f32 v[250:251], v[128:129], v[192:193], v[250:251]
	v_cvt_pk_f32_fp8_sdwa v[128:129], v38 src0_sel:WORD_1
	v_pk_fma_f32 v[250:251], v[132:133], v[202:203], v[250:251]
	v_cvt_pk_f32_fp8_e32 v[132:133], v39
	v_pk_fma_f32 v[250:251], v[128:129], v[204:205], v[250:251]
	v_cvt_pk_f32_fp8_sdwa v[128:129], v39 src0_sel:WORD_1
	v_pk_fma_f32 v[250:251], v[132:133], v[206:207], v[250:251]
	global_load_dwordx4 v[36:39], v233, s[98:99]
	v_pk_fma_f32 v[250:251], v[128:129], v[208:209], v[250:251]
	v_cvt_pk_f32_fp8_sdwa v[130:131], v40 src0_sel:WORD_1
	v_add_f32_e32 v241, v250, v251
	v_cvt_pk_f32_fp8_e32 v[128:129], v40
	v_pk_mul_f32 v[130:131], v[130:131], v[188:189]
	v_cvt_pk_f32_fp8_e32 v[132:133], v41
	v_pk_fma_f32 v[250:251], v[128:129], v[186:187], v[130:131]
	v_cvt_pk_f32_fp8_sdwa v[128:129], v41 src0_sel:WORD_1
	v_pk_fma_f32 v[250:251], v[132:133], v[190:191], v[250:251]
	v_cvt_pk_f32_fp8_e32 v[132:133], v42
	v_pk_fma_f32 v[250:251], v[128:129], v[192:193], v[250:251]
	v_cvt_pk_f32_fp8_sdwa v[128:129], v42 src0_sel:WORD_1
	v_pk_fma_f32 v[250:251], v[132:133], v[202:203], v[250:251]
	v_cvt_pk_f32_fp8_e32 v[132:133], v43
	v_pk_fma_f32 v[250:251], v[128:129], v[204:205], v[250:251]
	v_cvt_pk_f32_fp8_sdwa v[128:129], v43 src0_sel:WORD_1
	v_pk_fma_f32 v[250:251], v[132:133], v[206:207], v[250:251]
	global_load_dwordx4 v[40:43], v234, s[98:99]
	v_pk_fma_f32 v[250:251], v[128:129], v[208:209], v[250:251]
	v_cvt_pk_f32_fp8_sdwa v[130:131], v44 src0_sel:WORD_1
	v_add_f32_e32 v242, v250, v251
	v_cvt_pk_f32_fp8_e32 v[128:129], v44
	v_pk_mul_f32 v[130:131], v[130:131], v[188:189]
	v_cvt_pk_f32_fp8_e32 v[132:133], v45
	v_pk_fma_f32 v[250:251], v[128:129], v[186:187], v[130:131]
	v_cvt_pk_f32_fp8_sdwa v[128:129], v45 src0_sel:WORD_1
	v_pk_fma_f32 v[250:251], v[132:133], v[190:191], v[250:251]
	v_cvt_pk_f32_fp8_e32 v[132:133], v46
	v_pk_fma_f32 v[250:251], v[128:129], v[192:193], v[250:251]
	v_cvt_pk_f32_fp8_sdwa v[128:129], v46 src0_sel:WORD_1
	v_pk_fma_f32 v[250:251], v[132:133], v[202:203], v[250:251]
	v_cvt_pk_f32_fp8_e32 v[132:133], v47
	v_pk_fma_f32 v[250:251], v[128:129], v[204:205], v[250:251]
	v_cvt_pk_f32_fp8_sdwa v[128:129], v47 src0_sel:WORD_1
	v_pk_fma_f32 v[250:251], v[132:133], v[206:207], v[250:251]
	global_load_dwordx4 v[44:47], v235, s[98:99]
	v_pk_fma_f32 v[250:251], v[128:129], v[208:209], v[250:251]
	v_cvt_pk_f32_fp8_sdwa v[130:131], v48 src0_sel:WORD_1
	v_add_f32_e32 v243, v250, v251
	v_cvt_pk_f32_fp8_e32 v[128:129], v48
	v_pk_mul_f32 v[130:131], v[130:131], v[188:189]
	v_cvt_pk_f32_fp8_e32 v[132:133], v49
	v_pk_fma_f32 v[250:251], v[128:129], v[186:187], v[130:131]
	v_cvt_pk_f32_fp8_sdwa v[128:129], v49 src0_sel:WORD_1
	v_pk_fma_f32 v[250:251], v[132:133], v[190:191], v[250:251]
	v_cvt_pk_f32_fp8_e32 v[132:133], v50
	v_pk_fma_f32 v[250:251], v[128:129], v[192:193], v[250:251]
	v_cvt_pk_f32_fp8_sdwa v[128:129], v50 src0_sel:WORD_1
	v_pk_fma_f32 v[250:251], v[132:133], v[202:203], v[250:251]
	v_cvt_pk_f32_fp8_e32 v[132:133], v51
	v_pk_fma_f32 v[250:251], v[128:129], v[204:205], v[250:251]
	v_cvt_pk_f32_fp8_sdwa v[128:129], v51 src0_sel:WORD_1
	v_pk_fma_f32 v[250:251], v[132:133], v[206:207], v[250:251]
	global_load_dwordx4 v[48:51], v236, s[98:99]
	v_pk_fma_f32 v[250:251], v[128:129], v[208:209], v[250:251]
	v_cvt_pk_f32_fp8_sdwa v[130:131], v52 src0_sel:WORD_1
	v_add_f32_e32 v244, v250, v251
	v_cvt_pk_f32_fp8_e32 v[128:129], v52
	v_pk_mul_f32 v[130:131], v[130:131], v[188:189]
	v_cvt_pk_f32_fp8_e32 v[132:133], v53
	v_pk_fma_f32 v[250:251], v[128:129], v[186:187], v[130:131]
	v_cvt_pk_f32_fp8_sdwa v[128:129], v53 src0_sel:WORD_1
	v_pk_fma_f32 v[250:251], v[132:133], v[190:191], v[250:251]
	v_cvt_pk_f32_fp8_e32 v[132:133], v54
	v_pk_fma_f32 v[250:251], v[128:129], v[192:193], v[250:251]
	v_cvt_pk_f32_fp8_sdwa v[128:129], v54 src0_sel:WORD_1
	v_pk_fma_f32 v[250:251], v[132:133], v[202:203], v[250:251]
	v_cvt_pk_f32_fp8_e32 v[132:133], v55
	v_pk_fma_f32 v[250:251], v[128:129], v[204:205], v[250:251]
	v_cvt_pk_f32_fp8_sdwa v[128:129], v55 src0_sel:WORD_1
	v_pk_fma_f32 v[250:251], v[132:133], v[206:207], v[250:251]
	global_load_dwordx4 v[52:55], v237, s[98:99]
	v_pk_fma_f32 v[250:251], v[128:129], v[208:209], v[250:251]
	v_cvt_pk_f32_fp8_sdwa v[130:131], v64 src0_sel:WORD_1
	v_add_f32_e32 v245, v250, v251
	v_add_f32_dpp v240, v240, v240 row_half_mirror row_mask:0xf bank_mask:0x5
	v_add_f32_dpp v240, v244, v244 row_half_mirror row_mask:0xf bank_mask:0xa
	v_cvt_pk_f32_fp8_e32 v[128:129], v64
	v_pk_mul_f32 v[130:131], v[130:131], v[188:189]
	v_cvt_pk_f32_fp8_e32 v[132:133], v65
	v_pk_fma_f32 v[250:251], v[128:129], v[186:187], v[130:131]
	v_cvt_pk_f32_fp8_sdwa v[128:129], v65 src0_sel:WORD_1
	v_pk_fma_f32 v[250:251], v[132:133], v[190:191], v[250:251]
	v_cvt_pk_f32_fp8_e32 v[132:133], v66
	v_pk_fma_f32 v[250:251], v[128:129], v[192:193], v[250:251]
	v_cvt_pk_f32_fp8_sdwa v[128:129], v66 src0_sel:WORD_1
	v_pk_fma_f32 v[250:251], v[132:133], v[202:203], v[250:251]
	v_cvt_pk_f32_fp8_e32 v[132:133], v67
	v_pk_fma_f32 v[250:251], v[128:129], v[204:205], v[250:251]
	v_cvt_pk_f32_fp8_sdwa v[128:129], v67 src0_sel:WORD_1
	v_pk_fma_f32 v[250:251], v[132:133], v[206:207], v[250:251]
	global_load_dwordx4 v[64:67], v238, s[98:99]
	v_pk_fma_f32 v[250:251], v[128:129], v[208:209], v[250:251]
	v_cvt_pk_f32_fp8_sdwa v[130:131], v68 src0_sel:WORD_1
	v_add_f32_e32 v246, v250, v251
	v_add_f32_dpp v241, v241, v241 row_half_mirror row_mask:0xf bank_mask:0x5
	v_add_f32_dpp v241, v245, v245 row_half_mirror row_mask:0xf bank_mask:0xa
	v_add_f32_dpp v242, v242, v242 row_half_mirror row_mask:0xf bank_mask:0x5
	v_add_f32_dpp v242, v246, v246 row_half_mirror row_mask:0xf bank_mask:0xa
	v_add_f32_dpp v240, v240, v240 quad_perm:[2,3,0,1] row_mask:0xf bank_mask:0xf
	v_add_f32_dpp v241, v241, v241 quad_perm:[2,3,0,1] row_mask:0xf bank_mask:0xf
	v_add_f32_dpp v242, v242, v242 quad_perm:[2,3,0,1] row_mask:0xf bank_mask:0xf
	v_cndmask_b32_e64 v240, v240, v242, s[40:41]
	v_cvt_pk_f32_fp8_e32 v[128:129], v68
	v_pk_mul_f32 v[130:131], v[130:131], v[188:189]
	v_cvt_pk_f32_fp8_e32 v[132:133], v69
	v_pk_fma_f32 v[250:251], v[128:129], v[186:187], v[130:131]
	v_cvt_pk_f32_fp8_sdwa v[128:129], v69 src0_sel:WORD_1
	v_pk_fma_f32 v[250:251], v[132:133], v[190:191], v[250:251]
	v_cvt_pk_f32_fp8_e32 v[132:133], v70
	v_pk_fma_f32 v[250:251], v[128:129], v[192:193], v[250:251]
	v_cvt_pk_f32_fp8_sdwa v[128:129], v70 src0_sel:WORD_1
	v_pk_fma_f32 v[250:251], v[132:133], v[202:203], v[250:251]
	v_cvt_pk_f32_fp8_e32 v[132:133], v71
	v_pk_fma_f32 v[250:251], v[128:129], v[204:205], v[250:251]
	v_cvt_pk_f32_fp8_sdwa v[128:129], v71 src0_sel:WORD_1
	v_pk_fma_f32 v[250:251], v[132:133], v[206:207], v[250:251]
	global_load_dwordx4 v[68:71], v239, s[98:99]
	v_pk_fma_f32 v[250:251], v[128:129], v[208:209], v[250:251]
	s_nop 0
	v_add_f32_e32 v247, v250, v251
	v_add_f32_dpp v240, v240, v240 quad_perm:[1,0,3,2] row_mask:0xf bank_mask:0xf
	v_add_f32_dpp v243, v243, v243 row_half_mirror row_mask:0xf bank_mask:0x5
	v_add_f32_dpp v243, v247, v247 row_half_mirror row_mask:0xf bank_mask:0xa
	s_nop 1
	v_add_f32_dpp v243, v243, v243 quad_perm:[2,3,0,1] row_mask:0xf bank_mask:0xf
	v_cndmask_b32_e64 v241, v241, v243, s[40:41]
	s_nop 1
	v_add_f32_dpp v241, v241, v241 quad_perm:[1,0,3,2] row_mask:0xf bank_mask:0xf
	v_cndmask_b32_e64 v249, v240, v241, s[4:5]
	s_mov_b32 s29, s26
	s_lshl_b32 s29, s29, 9
	s_add_u32 s2, s46, s29
	s_addc_u32 s3, s47, 0
	global_store_dword v135, v248, s[2:3]
	global_store_dword v135, v249, s[2:3] offset:256
	s_waitcnt vmcnt(18)
	ds_bpermute_b32 v224, v157, v177
	ds_bpermute_b32 v225, v194, v177
	ds_bpermute_b32 v226, v196, v177
	ds_bpermute_b32 v227, v197, v177
	ds_bpermute_b32 v228, v198, v177
	ds_bpermute_b32 v229, v199, v177
	ds_bpermute_b32 v230, v200, v177
	ds_bpermute_b32 v231, v201, v177
	ds_bpermute_b32 v232, v157, v195
	ds_bpermute_b32 v233, v194, v195
	ds_bpermute_b32 v234, v196, v195
	ds_bpermute_b32 v235, v197, v195
	ds_bpermute_b32 v236, v198, v195
	ds_bpermute_b32 v237, v199, v195
	ds_bpermute_b32 v238, v200, v195
	ds_bpermute_b32 v239, v201, v195
	v_lshlrev_b32_e32 v186, 16, v140
	v_and_b32_e32 v187, 0xffff0000, v140
	v_lshlrev_b32_e32 v188, 16, v141
	v_and_b32_e32 v189, 0xffff0000, v141
	v_lshlrev_b32_e32 v190, 16, v142
	v_and_b32_e32 v191, 0xffff0000, v142
	v_lshlrev_b32_e32 v192, 16, v143
	v_and_b32_e32 v193, 0xffff0000, v143
	v_lshlrev_b32_e32 v202, 16, v136
	v_and_b32_e32 v203, 0xffff0000, v136
	v_lshlrev_b32_e32 v204, 16, v137
	v_and_b32_e32 v205, 0xffff0000, v137
	v_lshlrev_b32_e32 v206, 16, v138
	v_and_b32_e32 v207, 0xffff0000, v138
	v_lshlrev_b32_e32 v208, 16, v139
	v_and_b32_e32 v209, 0xffff0000, v139
	s_waitcnt lgkmcnt(0)
	v_lshl_add_u32 v224, v224, 7, v255
	v_lshl_add_u32 v225, v225, 7, v255
	v_lshl_add_u32 v226, v226, 7, v255
	v_lshl_add_u32 v227, v227, 7, v255
	v_lshl_add_u32 v228, v228, 7, v255
	v_lshl_add_u32 v229, v229, 7, v255
	v_lshl_add_u32 v230, v230, 7, v255
	v_lshl_add_u32 v231, v231, 7, v255
	v_lshl_add_u32 v232, v232, 7, v255
	v_lshl_add_u32 v233, v233, 7, v255
	v_lshl_add_u32 v234, v234, 7, v255
	v_lshl_add_u32 v235, v235, 7, v255
	v_lshl_add_u32 v236, v236, 7, v255
	v_lshl_add_u32 v237, v237, 7, v255
	v_lshl_add_u32 v238, v238, 7, v255
	v_lshl_add_u32 v239, v239, 7, v255
	s_add_u32 s29, s26, 0x200
	s_min_u32 s29, s29, s27
	s_add_u32 s29, s29, 0x100
	s_lshl_b32 s29, s29, 11
	s_add_u32 s2, s94, s29
	s_addc_u32 s3, s95, 0
	global_load_dwordx4 v[140:143], v134, s[2:3]
	global_load_dwordx4 v[136:139], v134, s[2:3] offset:16
	s_add_u32 s29, s26, 0x400
	s_min_u32 s29, s29, s27
	s_lshl_b32 s29, s29, 9
	s_add_u32 s2, s38, s29
	s_addc_u32 s3, s39, 0
	global_load_dword v159, v172, s[2:3]
	global_load_dword v161, v172, s[2:3] offset:256
	v_cvt_pk_f32_fp8_sdwa v[130:131], v56 src0_sel:WORD_1
	v_cvt_pk_f32_fp8_e32 v[128:129], v56
	v_pk_mul_f32 v[130:131], v[130:131], v[188:189]
	v_cvt_pk_f32_fp8_e32 v[132:133], v57
	v_pk_fma_f32 v[250:251], v[128:129], v[186:187], v[130:131]
	v_cvt_pk_f32_fp8_sdwa v[128:129], v57 src0_sel:WORD_1
	v_pk_fma_f32 v[250:251], v[132:133], v[190:191], v[250:251]
	v_cvt_pk_f32_fp8_e32 v[132:133], v58
	v_pk_fma_f32 v[250:251], v[128:129], v[192:193], v[250:251]
	v_cvt_pk_f32_fp8_sdwa v[128:129], v58 src0_sel:WORD_1
	v_pk_fma_f32 v[250:251], v[132:133], v[202:203], v[250:251]
	v_cvt_pk_f32_fp8_e32 v[132:133], v59
	v_pk_fma_f32 v[250:251], v[128:129], v[204:205], v[250:251]
	v_cvt_pk_f32_fp8_sdwa v[128:129], v59 src0_sel:WORD_1
	v_pk_fma_f32 v[250:251], v[132:133], v[206:207], v[250:251]
	global_load_dwordx4 v[56:59], v224, s[98:99]
	v_pk_fma_f32 v[250:251], v[128:129], v[208:209], v[250:251]
	v_cvt_pk_f32_fp8_sdwa v[130:131], v60 src0_sel:WORD_1
	v_add_f32_e32 v240, v250, v251
	v_cvt_pk_f32_fp8_e32 v[128:129], v60
	v_pk_mul_f32 v[130:131], v[130:131], v[188:189]
	v_cvt_pk_f32_fp8_e32 v[132:133], v61
	v_pk_fma_f32 v[250:251], v[128:129], v[186:187], v[130:131]
	v_cvt_pk_f32_fp8_sdwa v[128:129], v61 src0_sel:WORD_1
	v_pk_fma_f32 v[250:251], v[132:133], v[190:191], v[250:251]
	v_cvt_pk_f32_fp8_e32 v[132:133], v62
	v_pk_fma_f32 v[250:251], v[128:129], v[192:193], v[250:251]
	v_cvt_pk_f32_fp8_sdwa v[128:129], v62 src0_sel:WORD_1
	v_pk_fma_f32 v[250:251], v[132:133], v[202:203], v[250:251]
	v_cvt_pk_f32_fp8_e32 v[132:133], v63
	v_pk_fma_f32 v[250:251], v[128:129], v[204:205], v[250:251]
	v_cvt_pk_f32_fp8_sdwa v[128:129], v63 src0_sel:WORD_1
	v_pk_fma_f32 v[250:251], v[132:133], v[206:207], v[250:251]
	global_load_dwordx4 v[60:63], v225, s[98:99]
	v_pk_fma_f32 v[250:251], v[128:129], v[208:209], v[250:251]
	v_cvt_pk_f32_fp8_sdwa v[130:131], v72 src0_sel:WORD_1
	v_add_f32_e32 v241, v250, v251
	v_cvt_pk_f32_fp8_e32 v[128:129], v72
	v_pk_mul_f32 v[130:131], v[130:131], v[188:189]
	v_cvt_pk_f32_fp8_e32 v[132:133], v73
	v_pk_fma_f32 v[250:251], v[128:129], v[186:187], v[130:131]
	v_cvt_pk_f32_fp8_sdwa v[128:129], v73 src0_sel:WORD_1
	v_pk_fma_f32 v[250:251], v[132:133], v[190:191], v[250:251]
	v_cvt_pk_f32_fp8_e32 v[132:133], v74
	v_pk_fma_f32 v[250:251], v[128:129], v[192:193], v[250:251]
	v_cvt_pk_f32_fp8_sdwa v[128:129], v74 src0_sel:WORD_1
	v_pk_fma_f32 v[250:251], v[132:133], v[202:203], v[250:251]
	v_cvt_pk_f32_fp8_e32 v[132:133], v75
	v_pk_fma_f32 v[250:251], v[128:129], v[204:205], v[250:251]
	v_cvt_pk_f32_fp8_sdwa v[128:129], v75 src0_sel:WORD_1
	v_pk_fma_f32 v[250:251], v[132:133], v[206:207], v[250:251]
	global_load_dwordx4 v[72:75], v226, s[98:99]
	v_pk_fma_f32 v[250:251], v[128:129], v[208:209], v[250:251]
	v_cvt_pk_f32_fp8_sdwa v[130:131], v76 src0_sel:WORD_1
	v_add_f32_e32 v242, v250, v251
	v_cvt_pk_f32_fp8_e32 v[128:129], v76
	v_pk_mul_f32 v[130:131], v[130:131], v[188:189]
	v_cvt_pk_f32_fp8_e32 v[132:133], v77
	v_pk_fma_f32 v[250:251], v[128:129], v[186:187], v[130:131]
	v_cvt_pk_f32_fp8_sdwa v[128:129], v77 src0_sel:WORD_1
	v_pk_fma_f32 v[250:251], v[132:133], v[190:191], v[250:251]
	v_cvt_pk_f32_fp8_e32 v[132:133], v78
	v_pk_fma_f32 v[250:251], v[128:129], v[192:193], v[250:251]
	v_cvt_pk_f32_fp8_sdwa v[128:129], v78 src0_sel:WORD_1
	v_pk_fma_f32 v[250:251], v[132:133], v[202:203], v[250:251]
	v_cvt_pk_f32_fp8_e32 v[132:133], v79
	v_pk_fma_f32 v[250:251], v[128:129], v[204:205], v[250:251]
	v_cvt_pk_f32_fp8_sdwa v[128:129], v79 src0_sel:WORD_1
	v_pk_fma_f32 v[250:251], v[132:133], v[206:207], v[250:251]
	global_load_dwordx4 v[76:79], v227, s[98:99]
	v_pk_fma_f32 v[250:251], v[128:129], v[208:209], v[250:251]
	v_cvt_pk_f32_fp8_sdwa v[130:131], v80 src0_sel:WORD_1
	v_add_f32_e32 v243, v250, v251
	v_cvt_pk_f32_fp8_e32 v[128:129], v80
	v_pk_mul_f32 v[130:131], v[130:131], v[188:189]
	v_cvt_pk_f32_fp8_e32 v[132:133], v81
	v_pk_fma_f32 v[250:251], v[128:129], v[186:187], v[130:131]
	v_cvt_pk_f32_fp8_sdwa v[128:129], v81 src0_sel:WORD_1
	v_pk_fma_f32 v[250:251], v[132:133], v[190:191], v[250:251]
	v_cvt_pk_f32_fp8_e32 v[132:133], v82
	v_pk_fma_f32 v[250:251], v[128:129], v[192:193], v[250:251]
	v_cvt_pk_f32_fp8_sdwa v[128:129], v82 src0_sel:WORD_1
	v_pk_fma_f32 v[250:251], v[132:133], v[202:203], v[250:251]
	v_cvt_pk_f32_fp8_e32 v[132:133], v83
	v_pk_fma_f32 v[250:251], v[128:129], v[204:205], v[250:251]
	v_cvt_pk_f32_fp8_sdwa v[128:129], v83 src0_sel:WORD_1
	v_pk_fma_f32 v[250:251], v[132:133], v[206:207], v[250:251]
	global_load_dwordx4 v[80:83], v228, s[98:99]
	v_pk_fma_f32 v[250:251], v[128:129], v[208:209], v[250:251]
	v_cvt_pk_f32_fp8_sdwa v[130:131], v84 src0_sel:WORD_1
	v_add_f32_e32 v244, v250, v251
	v_cvt_pk_f32_fp8_e32 v[128:129], v84
	v_pk_mul_f32 v[130:131], v[130:131], v[188:189]
	v_cvt_pk_f32_fp8_e32 v[132:133], v85
	v_pk_fma_f32 v[250:251], v[128:129], v[186:187], v[130:131]
	v_cvt_pk_f32_fp8_sdwa v[128:129], v85 src0_sel:WORD_1
	v_pk_fma_f32 v[250:251], v[132:133], v[190:191], v[250:251]
	v_cvt_pk_f32_fp8_e32 v[132:133], v86
	v_pk_fma_f32 v[250:251], v[128:129], v[192:193], v[250:251]
	v_cvt_pk_f32_fp8_sdwa v[128:129], v86 src0_sel:WORD_1
	v_pk_fma_f32 v[250:251], v[132:133], v[202:203], v[250:251]
	v_cvt_pk_f32_fp8_e32 v[132:133], v87
	v_pk_fma_f32 v[250:251], v[128:129], v[204:205], v[250:251]
	v_cvt_pk_f32_fp8_sdwa v[128:129], v87 src0_sel:WORD_1
	v_pk_fma_f32 v[250:251], v[132:133], v[206:207], v[250:251]
	global_load_dwordx4 v[84:87], v229, s[98:99]
	v_pk_fma_f32 v[250:251], v[128:129], v[208:209], v[250:251]
	v_cvt_pk_f32_fp8_sdwa v[130:131], v88 src0_sel:WORD_1
	v_add_f32_e32 v245, v250, v251
	v_add_f32_dpp v240, v240, v240 row_half_mirror row_mask:0xf bank_mask:0x5
	v_add_f32_dpp v240, v244, v244 row_half_mirror row_mask:0xf bank_mask:0xa
	v_cvt_pk_f32_fp8_e32 v[128:129], v88
	v_pk_mul_f32 v[130:131], v[130:131], v[188:189]
	v_cvt_pk_f32_fp8_e32 v[132:133], v89
	v_pk_fma_f32 v[250:251], v[128:129], v[186:187], v[130:131]
	v_cvt_pk_f32_fp8_sdwa v[128:129], v89 src0_sel:WORD_1
	v_pk_fma_f32 v[250:251], v[132:133], v[190:191], v[250:251]
	v_cvt_pk_f32_fp8_e32 v[132:133], v90
	v_pk_fma_f32 v[250:251], v[128:129], v[192:193], v[250:251]
	v_cvt_pk_f32_fp8_sdwa v[128:129], v90 src0_sel:WORD_1
	v_pk_fma_f32 v[250:251], v[132:133], v[202:203], v[250:251]
	v_cvt_pk_f32_fp8_e32 v[132:133], v91
	v_pk_fma_f32 v[250:251], v[128:129], v[204:205], v[250:251]
	v_cvt_pk_f32_fp8_sdwa v[128:129], v91 src0_sel:WORD_1
	v_pk_fma_f32 v[250:251], v[132:133], v[206:207], v[250:251]
	global_load_dwordx4 v[88:91], v230, s[98:99]
	v_pk_fma_f32 v[250:251], v[128:129], v[208:209], v[250:251]
	v_cvt_pk_f32_fp8_sdwa v[130:131], v92 src0_sel:WORD_1
	v_add_f32_e32 v246, v250, v251
	v_add_f32_dpp v241, v241, v241 row_half_mirror row_mask:0xf bank_mask:0x5
	v_add_f32_dpp v241, v245, v245 row_half_mirror row_mask:0xf bank_mask:0xa
	v_cvt_pk_f32_fp8_e32 v[128:129], v92
	v_pk_mul_f32 v[130:131], v[130:131], v[188:189]
	v_cvt_pk_f32_fp8_e32 v[132:133], v93
	v_pk_fma_f32 v[250:251], v[128:129], v[186:187], v[130:131]
	v_cvt_pk_f32_fp8_sdwa v[128:129], v93 src0_sel:WORD_1
	v_pk_fma_f32 v[250:251], v[132:133], v[190:191], v[250:251]
	v_cvt_pk_f32_fp8_e32 v[132:133], v94
	v_pk_fma_f32 v[250:251], v[128:129], v[192:193], v[250:251]
	v_cvt_pk_f32_fp8_sdwa v[128:129], v94 src0_sel:WORD_1
	v_pk_fma_f32 v[250:251], v[132:133], v[202:203], v[250:251]
	v_cvt_pk_f32_fp8_e32 v[132:133], v95
	v_pk_fma_f32 v[250:251], v[128:129], v[204:205], v[250:251]
	v_cvt_pk_f32_fp8_sdwa v[128:129], v95 src0_sel:WORD_1
	v_pk_fma_f32 v[250:251], v[132:133], v[206:207], v[250:251]
	global_load_dwordx4 v[92:95], v231, s[98:99]
	v_pk_fma_f32 v[250:251], v[128:129], v[208:209], v[250:251]
	v_cvt_pk_f32_fp8_sdwa v[130:131], v96 src0_sel:WORD_1
	v_add_f32_e32 v247, v250, v251
	v_add_f32_dpp v242, v242, v242 row_half_mirror row_mask:0xf bank_mask:0x5
	v_add_f32_dpp v242, v246, v246 row_half_mirror row_mask:0xf bank_mask:0xa
	v_add_f32_dpp v243, v243, v243 row_half_mirror row_mask:0xf bank_mask:0x5
	v_add_f32_dpp v243, v247, v247 row_half_mirror row_mask:0xf bank_mask:0xa
	v_add_f32_dpp v240, v240, v240 quad_perm:[2,3,0,1] row_mask:0xf bank_mask:0xf
	v_add_f32_dpp v242, v242, v242 quad_perm:[2,3,0,1] row_mask:0xf bank_mask:0xf
	v_add_f32_dpp v241, v241, v241 quad_perm:[2,3,0,1] row_mask:0xf bank_mask:0xf
	v_cndmask_b32_e64 v240, v240, v242, s[40:41]
	v_add_f32_dpp v243, v243, v243 quad_perm:[2,3,0,1] row_mask:0xf bank_mask:0xf
	v_cndmask_b32_e64 v241, v241, v243, s[40:41]
	v_add_f32_dpp v240, v240, v240 quad_perm:[1,0,3,2] row_mask:0xf bank_mask:0xf
	s_nop 0
	v_add_f32_dpp v241, v241, v241 quad_perm:[1,0,3,2] row_mask:0xf bank_mask:0xf
	v_cndmask_b32_e64 v248, v240, v241, s[4:5]
	v_cvt_pk_f32_fp8_e32 v[128:129], v96
	v_pk_mul_f32 v[130:131], v[130:131], v[188:189]
	v_cvt_pk_f32_fp8_e32 v[132:133], v97
	v_pk_fma_f32 v[250:251], v[128:129], v[186:187], v[130:131]
	v_cvt_pk_f32_fp8_sdwa v[128:129], v97 src0_sel:WORD_1
	v_pk_fma_f32 v[250:251], v[132:133], v[190:191], v[250:251]
	v_cvt_pk_f32_fp8_e32 v[132:133], v98
	v_pk_fma_f32 v[250:251], v[128:129], v[192:193], v[250:251]
	v_cvt_pk_f32_fp8_sdwa v[128:129], v98 src0_sel:WORD_1
	v_pk_fma_f32 v[250:251], v[132:133], v[202:203], v[250:251]
	v_cvt_pk_f32_fp8_e32 v[132:133], v99
	v_pk_fma_f32 v[250:251], v[128:129], v[204:205], v[250:251]
	v_cvt_pk_f32_fp8_sdwa v[128:129], v99 src0_sel:WORD_1
	v_pk_fma_f32 v[250:251], v[132:133], v[206:207], v[250:251]
	global_load_dwordx4 v[96:99], v232, s[98:99]
	v_pk_fma_f32 v[250:251], v[128:129], v[208:209], v[250:251]
	v_cvt_pk_f32_fp8_sdwa v[130:131], v100 src0_sel:WORD_1
	v_add_f32_e32 v240, v250, v251
	v_cvt_pk_f32_fp8_e32 v[128:129], v100
	v_pk_mul_f32 v[130:131], v[130:131], v[188:189]
	v_cvt_pk_f32_fp8_e32 v[132:133], v101
	v_pk_fma_f32 v[250:251], v[128:129], v[186:187], v[130:131]
	v_cvt_pk_f32_fp8_sdwa v[128:129], v101 src0_sel:WORD_1
	v_pk_fma_f32 v[250:251], v[132:133], v[190:191], v[250:251]
	v_cvt_pk_f32_fp8_e32 v[132:133], v102
	v_pk_fma_f32 v[250:251], v[128:129], v[192:193], v[250:251]
	v_cvt_pk_f32_fp8_sdwa v[128:129], v102 src0_sel:WORD_1
	v_pk_fma_f32 v[250:251], v[132:133], v[202:203], v[250:251]
	v_cvt_pk_f32_fp8_e32 v[132:133], v103
	v_pk_fma_f32 v[250:251], v[128:129], v[204:205], v[250:251]
	v_cvt_pk_f32_fp8_sdwa v[128:129], v103 src0_sel:WORD_1
	v_pk_fma_f32 v[250:251], v[132:133], v[206:207], v[250:251]
	global_load_dwordx4 v[100:103], v233, s[98:99]
	v_pk_fma_f32 v[250:251], v[128:129], v[208:209], v[250:251]
	v_cvt_pk_f32_fp8_sdwa v[130:131], v104 src0_sel:WORD_1
	v_add_f32_e32 v241, v250, v251
	v_cvt_pk_f32_fp8_e32 v[128:129], v104
	v_pk_mul_f32 v[130:131], v[130:131], v[188:189]
	v_cvt_pk_f32_fp8_e32 v[132:133], v105
	v_pk_fma_f32 v[250:251], v[128:129], v[186:187], v[130:131]
	v_cvt_pk_f32_fp8_sdwa v[128:129], v105 src0_sel:WORD_1
	v_pk_fma_f32 v[250:251], v[132:133], v[190:191], v[250:251]
	v_cvt_pk_f32_fp8_e32 v[132:133], v106
	v_pk_fma_f32 v[250:251], v[128:129], v[192:193], v[250:251]
	v_cvt_pk_f32_fp8_sdwa v[128:129], v106 src0_sel:WORD_1
	v_pk_fma_f32 v[250:251], v[132:133], v[202:203], v[250:251]
	v_cvt_pk_f32_fp8_e32 v[132:133], v107
	v_pk_fma_f32 v[250:251], v[128:129], v[204:205], v[250:251]
	v_cvt_pk_f32_fp8_sdwa v[128:129], v107 src0_sel:WORD_1
	v_pk_fma_f32 v[250:251], v[132:133], v[206:207], v[250:251]
	global_load_dwordx4 v[104:107], v234, s[98:99]
	v_pk_fma_f32 v[250:251], v[128:129], v[208:209], v[250:251]
	v_cvt_pk_f32_fp8_sdwa v[130:131], v108 src0_sel:WORD_1
	v_add_f32_e32 v242, v250, v251
	v_cvt_pk_f32_fp8_e32 v[128:129], v108
	v_pk_mul_f32 v[130:131], v[130:131], v[188:189]
	v_cvt_pk_f32_fp8_e32 v[132:133], v109
	v_pk_fma_f32 v[250:251], v[128:129], v[186:187], v[130:131]
	v_cvt_pk_f32_fp8_sdwa v[128:129], v109 src0_sel:WORD_1
	v_pk_fma_f32 v[250:251], v[132:133], v[190:191], v[250:251]
	v_cvt_pk_f32_fp8_e32 v[132:133], v110
	v_pk_fma_f32 v[250:251], v[128:129], v[192:193], v[250:251]
	v_cvt_pk_f32_fp8_sdwa v[128:129], v110 src0_sel:WORD_1
	v_pk_fma_f32 v[250:251], v[132:133], v[202:203], v[250:251]
	v_cvt_pk_f32_fp8_e32 v[132:133], v111
	v_pk_fma_f32 v[250:251], v[128:129], v[204:205], v[250:251]
	v_cvt_pk_f32_fp8_sdwa v[128:129], v111 src0_sel:WORD_1
	v_pk_fma_f32 v[250:251], v[132:133], v[206:207], v[250:251]
	global_load_dwordx4 v[108:111], v235, s[98:99]
	v_pk_fma_f32 v[250:251], v[128:129], v[208:209], v[250:251]
	v_cvt_pk_f32_fp8_sdwa v[130:131], v112 src0_sel:WORD_1
	v_add_f32_e32 v243, v250, v251
	v_cvt_pk_f32_fp8_e32 v[128:129], v112
	v_pk_mul_f32 v[130:131], v[130:131], v[188:189]
	v_cvt_pk_f32_fp8_e32 v[132:133], v113
	v_pk_fma_f32 v[250:251], v[128:129], v[186:187], v[130:131]
	v_cvt_pk_f32_fp8_sdwa v[128:129], v113 src0_sel:WORD_1
	v_pk_fma_f32 v[250:251], v[132:133], v[190:191], v[250:251]
	v_cvt_pk_f32_fp8_e32 v[132:133], v114
	v_pk_fma_f32 v[250:251], v[128:129], v[192:193], v[250:251]
	v_cvt_pk_f32_fp8_sdwa v[128:129], v114 src0_sel:WORD_1
	v_pk_fma_f32 v[250:251], v[132:133], v[202:203], v[250:251]
	v_cvt_pk_f32_fp8_e32 v[132:133], v115
	v_pk_fma_f32 v[250:251], v[128:129], v[204:205], v[250:251]
	v_cvt_pk_f32_fp8_sdwa v[128:129], v115 src0_sel:WORD_1
	v_pk_fma_f32 v[250:251], v[132:133], v[206:207], v[250:251]
	global_load_dwordx4 v[112:115], v236, s[98:99]
	v_pk_fma_f32 v[250:251], v[128:129], v[208:209], v[250:251]
	v_cvt_pk_f32_fp8_sdwa v[130:131], v116 src0_sel:WORD_1
	v_add_f32_e32 v244, v250, v251
	v_cvt_pk_f32_fp8_e32 v[128:129], v116
	v_pk_mul_f32 v[130:131], v[130:131], v[188:189]
	v_cvt_pk_f32_fp8_e32 v[132:133], v117
	v_pk_fma_f32 v[250:251], v[128:129], v[186:187], v[130:131]
	v_cvt_pk_f32_fp8_sdwa v[128:129], v117 src0_sel:WORD_1
	v_pk_fma_f32 v[250:251], v[132:133], v[190:191], v[250:251]
	v_cvt_pk_f32_fp8_e32 v[132:133], v118
	v_pk_fma_f32 v[250:251], v[128:129], v[192:193], v[250:251]
	v_cvt_pk_f32_fp8_sdwa v[128:129], v118 src0_sel:WORD_1
	v_pk_fma_f32 v[250:251], v[132:133], v[202:203], v[250:251]
	v_cvt_pk_f32_fp8_e32 v[132:133], v119
	v_pk_fma_f32 v[250:251], v[128:129], v[204:205], v[250:251]
	v_cvt_pk_f32_fp8_sdwa v[128:129], v119 src0_sel:WORD_1
	v_pk_fma_f32 v[250:251], v[132:133], v[206:207], v[250:251]
	global_load_dwordx4 v[116:119], v237, s[98:99]
	v_pk_fma_f32 v[250:251], v[128:129], v[208:209], v[250:251]
	v_cvt_pk_f32_fp8_sdwa v[130:131], v120 src0_sel:WORD_1
	v_add_f32_e32 v245, v250, v251
	v_add_f32_dpp v240, v240, v240 row_half_mirror row_mask:0xf bank_mask:0x5
	v_add_f32_dpp v240, v244, v244 row_half_mirror row_mask:0xf bank_mask:0xa
	v_cvt_pk_f32_fp8_e32 v[128:129], v120
	v_pk_mul_f32 v[130:131], v[130:131], v[188:189]
	v_cvt_pk_f32_fp8_e32 v[132:133], v121
	v_pk_fma_f32 v[250:251], v[128:129], v[186:187], v[130:131]
	v_cvt_pk_f32_fp8_sdwa v[128:129], v121 src0_sel:WORD_1
	v_pk_fma_f32 v[250:251], v[132:133], v[190:191], v[250:251]
	v_cvt_pk_f32_fp8_e32 v[132:133], v122
	v_pk_fma_f32 v[250:251], v[128:129], v[192:193], v[250:251]
	v_cvt_pk_f32_fp8_sdwa v[128:129], v122 src0_sel:WORD_1
	v_pk_fma_f32 v[250:251], v[132:133], v[202:203], v[250:251]
	v_cvt_pk_f32_fp8_e32 v[132:133], v123
	v_pk_fma_f32 v[250:251], v[128:129], v[204:205], v[250:251]
	v_cvt_pk_f32_fp8_sdwa v[128:129], v123 src0_sel:WORD_1
	v_pk_fma_f32 v[250:251], v[132:133], v[206:207], v[250:251]
	global_load_dwordx4 v[120:123], v238, s[98:99]
	v_pk_fma_f32 v[250:251], v[128:129], v[208:209], v[250:251]
	v_cvt_pk_f32_fp8_sdwa v[130:131], v124 src0_sel:WORD_1
	v_add_f32_e32 v246, v250, v251
	v_add_f32_dpp v241, v241, v241 row_half_mirror row_mask:0xf bank_mask:0x5
	v_add_f32_dpp v241, v245, v245 row_half_mirror row_mask:0xf bank_mask:0xa
	v_add_f32_dpp v242, v242, v242 row_half_mirror row_mask:0xf bank_mask:0x5
	v_add_f32_dpp v242, v246, v246 row_half_mirror row_mask:0xf bank_mask:0xa
	v_add_f32_dpp v240, v240, v240 quad_perm:[2,3,0,1] row_mask:0xf bank_mask:0xf
	v_add_f32_dpp v241, v241, v241 quad_perm:[2,3,0,1] row_mask:0xf bank_mask:0xf
	v_add_f32_dpp v242, v242, v242 quad_perm:[2,3,0,1] row_mask:0xf bank_mask:0xf
	v_cndmask_b32_e64 v240, v240, v242, s[40:41]
	v_cvt_pk_f32_fp8_e32 v[128:129], v124
	v_pk_mul_f32 v[130:131], v[130:131], v[188:189]
	v_cvt_pk_f32_fp8_e32 v[132:133], v125
	v_pk_fma_f32 v[250:251], v[128:129], v[186:187], v[130:131]
	v_cvt_pk_f32_fp8_sdwa v[128:129], v125 src0_sel:WORD_1
	v_pk_fma_f32 v[250:251], v[132:133], v[190:191], v[250:251]
	v_cvt_pk_f32_fp8_e32 v[132:133], v126
	v_pk_fma_f32 v[250:251], v[128:129], v[192:193], v[250:251]
	v_cvt_pk_f32_fp8_sdwa v[128:129], v126 src0_sel:WORD_1
	v_pk_fma_f32 v[250:251], v[132:133], v[202:203], v[250:251]
	v_cvt_pk_f32_fp8_e32 v[132:133], v127
	v_pk_fma_f32 v[250:251], v[128:129], v[204:205], v[250:251]
	v_cvt_pk_f32_fp8_sdwa v[128:129], v127 src0_sel:WORD_1
	v_pk_fma_f32 v[250:251], v[132:133], v[206:207], v[250:251]
	global_load_dwordx4 v[124:127], v239, s[98:99]
	v_pk_fma_f32 v[250:251], v[128:129], v[208:209], v[250:251]
	s_nop 0
	v_add_f32_e32 v247, v250, v251
	v_add_f32_dpp v240, v240, v240 quad_perm:[1,0,3,2] row_mask:0xf bank_mask:0xf
	v_add_f32_dpp v243, v243, v243 row_half_mirror row_mask:0xf bank_mask:0x5
	v_add_f32_dpp v243, v247, v247 row_half_mirror row_mask:0xf bank_mask:0xa
	s_nop 1
	v_add_f32_dpp v243, v243, v243 quad_perm:[2,3,0,1] row_mask:0xf bank_mask:0xf
	v_cndmask_b32_e64 v241, v241, v243, s[40:41]
	s_nop 1
	v_add_f32_dpp v241, v241, v241 quad_perm:[1,0,3,2] row_mask:0xf bank_mask:0xf
	v_cndmask_b32_e64 v249, v240, v241, s[4:5]
	s_add_u32 s29, s26, 0x100
	s_lshl_b32 s29, s29, 9
	s_add_u32 s2, s46, s29
	s_addc_u32 s3, s47, 0
	global_store_dword v135, v248, s[2:3]
	global_store_dword v135, v249, s[2:3] offset:256
	s_add_u32 s26, s26, 0x200
	s_sub_u32 s28, s28, 1
	s_cmp_lg_u32 s28, 0
	s_cbranch_scc1 .Lpu1_loop
